# gates W-tile loads batched (8 in flight) + ckv_norm rows batched with DPP wave reduction
# speedup vs baseline: 1.0685x; 1.0035x over previous
.LBB0_288:
	s_andn2_b64 vcc, exec, s[0:1]
	s_cbranch_vccnz .LBB0_1456
	v_readlane_b32 s0, v252, 23
	s_cmp_lt_i32 s0, 3
	s_mov_b64 s[0:1], -1
	s_cbranch_scc1 .LBB0_1019
	v_readlane_b32 s0, v252, 23
	s_cmp_lt_i32 s0, 4
	s_mov_b64 s[0:1], -1
	s_cbranch_scc1 .LBB0_1003
	v_readlane_b32 s0, v252, 23
	s_cmp_gt_i32 s0, 4
	s_mov_b64 s[0:1], -1
	s_cbranch_scc0 .LBB0_624
	s_waitcnt vmcnt(7)
	v_mov_b32_e32 v0, v192
	s_waitcnt vmcnt(6)
	v_mov_b32_e32 v4, v192
	s_load_dwordx2 s[0:1], s[58:59], 0x60
	v_readlane_b32 s2, v252, 21
	v_readlane_b32 s3, v252, 22
	s_mov_b32 s4, s2
	s_ashr_i32 s5, s2, 31
	v_writelane_b32 v252, s2, 21
	v_lshlrev_b32_e32 v0, 2, v0
	v_and_b32_e32 v5, 0xfc, v0
	v_writelane_b32 v252, s3, 22
	s_lshl_b64 s[2:3], s[4:5], 10
	s_waitcnt lgkmcnt(0)
	s_add_u32 s0, s0, s2
	s_addc_u32 s1, s1, s3
	v_lshlrev_b32_e32 v176, 2, v5
	global_load_dwordx4 v[0:3], v176, s[0:1]
	s_load_dwordx2 s[2:3], s[58:59], 0xd8
	s_mov_b32 s0, s55
	v_ashrrev_i32_e32 v4, 6, v4
	s_nop 0
	v_lshl_add_u32 v4, s0, 2, v4
	s_movk_i32 s0, 0x4080
	v_cmp_gt_i32_e32 vcc, s0, v4
	s_and_saveexec_b64 s[0:1], vcc
	s_mov_b32 s7, 0x800000
	s_movk_i32 s8, 0x407f
	s_cbranch_execz .LBB0_295
	v_cmp_lt_i32_e32 vcc, v202, v201
	s_waitcnt lgkmcnt(0)
	v_lshl_add_u64 v[6:7], s[2:3], 0, v[176:177]
	v_lshlrev_b32_e32 v176, 1, v5
	v_cndmask_b32_e32 v5, v199, v202, vcc
	v_cmp_lt_i32_e32 vcc, v203, v201
	s_waitcnt vmcnt(6)
	v_lshlrev_b32_e32 v10, 2, v5
	s_mov_b64 s[4:5], 0x4820000
	v_cndmask_b32_e32 v5, v199, v203, vcc
	v_cmp_lt_i32_e32 vcc, v204, v201
	v_lshlrev_b32_e32 v11, 2, v5
	v_lshl_add_u64 v[6:7], v[6:7], 0, s[4:5]
	v_cndmask_b32_e32 v5, v199, v204, vcc
	v_cmp_lt_i32_e32 vcc, v205, v201
	s_waitcnt vmcnt(5)
	v_lshlrev_b32_e32 v12, 2, v5
	v_lshl_add_u64 v[8:9], s[2:3], 0, v[176:177]
	v_cndmask_b32_e32 v5, v199, v205, vcc
	v_cmp_lt_i32_e32 vcc, v206, v201
	v_lshlrev_b32_e32 v13, 2, v5
	s_mov_b64 s[4:5], 0x6860000
	v_cndmask_b32_e32 v5, v199, v206, vcc
	v_cmp_lt_i32_e32 vcc, v207, v201
	v_lshlrev_b32_e32 v14, 2, v5
	v_lshl_add_u64 v[8:9], v[8:9], 0, s[4:5]
	v_cndmask_b32_e32 v5, v199, v207, vcc
	v_lshlrev_b32_e32 v15, 2, v5
	s_mov_b64 s[4:5], 0
	s_cmp_lg_u32 s62, 0x200
	s_cbranch_scc1 .LBB0_294
	v_readfirstlane_b32 s6, v4
	v_ashrrev_i32_e32 v5, 31, v4
	v_lshlrev_b64 v[16:17], 10, v[4:5]
	v_lshl_add_u64 v[16:17], v[6:7], 0, v[16:17]
	s_mov_b32 s44, 0x200000
	s_mov_b32 s45, 0
	s_add_i32 s6, s6, 0x4000
	s_min_u32 s6, s6, s8
	s_lshl_b32 s52, s6, 10
	s_mov_b32 s53, 0
	global_load_dwordx4 v[20:23], v[16:17], off
	v_lshl_add_u64 v[16:17], v[16:17], 0, s[44:45]
	global_load_dwordx4 v[24:27], v[16:17], off
	v_lshl_add_u64 v[16:17], v[16:17], 0, s[44:45]
	global_load_dwordx4 v[28:31], v[16:17], off
	v_lshl_add_u64 v[16:17], v[16:17], 0, s[44:45]
	global_load_dwordx4 v[32:35], v[16:17], off
	v_lshl_add_u64 v[16:17], v[16:17], 0, s[44:45]
	global_load_dwordx4 v[36:39], v[16:17], off
	v_lshl_add_u64 v[16:17], v[16:17], 0, s[44:45]
	global_load_dwordx4 v[40:43], v[16:17], off
	v_lshl_add_u64 v[16:17], v[16:17], 0, s[44:45]
	global_load_dwordx4 v[44:47], v[16:17], off
	v_lshl_add_u64 v[16:17], v[16:17], 0, s[44:45]
	global_load_dwordx4 v[48:51], v[16:17], off
	v_lshl_add_u64 v[18:19], v[6:7], 0, s[52:53]
	global_load_dwordx4 v[52:55], v[18:19], off
	s_waitcnt vmcnt(8)
	v_pk_mul_f32 v[74:75], v[20:21], v[20:21]
	v_pk_mul_f32 v[76:77], v[22:23], v[22:23]
	v_add_f32_e32 v74, v74, v75
	v_add_f32_e32 v74, v76, v74
	v_add_f32_e32 v56, v77, v74
	s_waitcnt vmcnt(7)
	v_pk_mul_f32 v[74:75], v[24:25], v[24:25]
	v_pk_mul_f32 v[76:77], v[26:27], v[26:27]
	v_add_f32_e32 v74, v74, v75
	v_add_f32_e32 v74, v76, v74
	v_add_f32_e32 v57, v77, v74
	s_waitcnt vmcnt(6)
	v_pk_mul_f32 v[74:75], v[28:29], v[28:29]
	v_pk_mul_f32 v[76:77], v[30:31], v[30:31]
	v_add_f32_e32 v74, v74, v75
	v_add_f32_e32 v74, v76, v74
	v_add_f32_e32 v58, v77, v74
	s_waitcnt vmcnt(5)
	v_pk_mul_f32 v[74:75], v[32:33], v[32:33]
	v_pk_mul_f32 v[76:77], v[34:35], v[34:35]
	v_add_f32_e32 v74, v74, v75
	v_add_f32_e32 v74, v76, v74
	v_add_f32_e32 v59, v77, v74
	s_waitcnt vmcnt(4)
	v_pk_mul_f32 v[74:75], v[36:37], v[36:37]
	v_pk_mul_f32 v[76:77], v[38:39], v[38:39]
	v_add_f32_e32 v74, v74, v75
	v_add_f32_e32 v74, v76, v74
	v_add_f32_e32 v60, v77, v74
	s_waitcnt vmcnt(3)
	v_pk_mul_f32 v[74:75], v[40:41], v[40:41]
	v_pk_mul_f32 v[76:77], v[42:43], v[42:43]
	v_add_f32_e32 v74, v74, v75
	v_add_f32_e32 v74, v76, v74
	v_add_f32_e32 v61, v77, v74
	s_waitcnt vmcnt(2)
	v_pk_mul_f32 v[74:75], v[44:45], v[44:45]
	v_pk_mul_f32 v[76:77], v[46:47], v[46:47]
	v_add_f32_e32 v74, v74, v75
	v_add_f32_e32 v74, v76, v74
	v_add_f32_e32 v62, v77, v74
	s_waitcnt vmcnt(1)
	v_pk_mul_f32 v[74:75], v[48:49], v[48:49]
	v_pk_mul_f32 v[76:77], v[50:51], v[50:51]
	v_add_f32_e32 v74, v74, v75
	v_add_f32_e32 v74, v76, v74
	v_add_f32_e32 v63, v77, v74
	s_waitcnt vmcnt(0)
	v_pk_mul_f32 v[74:75], v[52:53], v[52:53]
	v_pk_mul_f32 v[76:77], v[54:55], v[54:55]
	v_add_f32_e32 v74, v74, v75
	v_add_f32_e32 v74, v76, v74
	v_add_f32_e32 v64, v77, v74
	v_add_f32_dpp v56, v56, v56 quad_perm:[1,0,3,2] row_mask:0xf bank_mask:0xf
	v_add_f32_dpp v57, v57, v57 quad_perm:[1,0,3,2] row_mask:0xf bank_mask:0xf
	v_add_f32_dpp v58, v58, v58 quad_perm:[1,0,3,2] row_mask:0xf bank_mask:0xf
	v_add_f32_dpp v59, v59, v59 quad_perm:[1,0,3,2] row_mask:0xf bank_mask:0xf
	v_add_f32_dpp v60, v60, v60 quad_perm:[1,0,3,2] row_mask:0xf bank_mask:0xf
	v_add_f32_dpp v61, v61, v61 quad_perm:[1,0,3,2] row_mask:0xf bank_mask:0xf
	v_add_f32_dpp v62, v62, v62 quad_perm:[1,0,3,2] row_mask:0xf bank_mask:0xf
	v_add_f32_dpp v63, v63, v63 quad_perm:[1,0,3,2] row_mask:0xf bank_mask:0xf
	v_add_f32_dpp v64, v64, v64 quad_perm:[1,0,3,2] row_mask:0xf bank_mask:0xf
	v_add_f32_dpp v56, v56, v56 quad_perm:[2,3,0,1] row_mask:0xf bank_mask:0xf
	v_add_f32_dpp v57, v57, v57 quad_perm:[2,3,0,1] row_mask:0xf bank_mask:0xf
	v_add_f32_dpp v58, v58, v58 quad_perm:[2,3,0,1] row_mask:0xf bank_mask:0xf
	v_add_f32_dpp v59, v59, v59 quad_perm:[2,3,0,1] row_mask:0xf bank_mask:0xf
	v_add_f32_dpp v60, v60, v60 quad_perm:[2,3,0,1] row_mask:0xf bank_mask:0xf
	v_add_f32_dpp v61, v61, v61 quad_perm:[2,3,0,1] row_mask:0xf bank_mask:0xf
	v_add_f32_dpp v62, v62, v62 quad_perm:[2,3,0,1] row_mask:0xf bank_mask:0xf
	v_add_f32_dpp v63, v63, v63 quad_perm:[2,3,0,1] row_mask:0xf bank_mask:0xf
	v_add_f32_dpp v64, v64, v64 quad_perm:[2,3,0,1] row_mask:0xf bank_mask:0xf
	v_add_f32_dpp v56, v56, v56 row_half_mirror row_mask:0xf bank_mask:0xf
	v_add_f32_dpp v57, v57, v57 row_half_mirror row_mask:0xf bank_mask:0xf
	v_add_f32_dpp v58, v58, v58 row_half_mirror row_mask:0xf bank_mask:0xf
	v_add_f32_dpp v59, v59, v59 row_half_mirror row_mask:0xf bank_mask:0xf
	v_add_f32_dpp v60, v60, v60 row_half_mirror row_mask:0xf bank_mask:0xf
	v_add_f32_dpp v61, v61, v61 row_half_mirror row_mask:0xf bank_mask:0xf
	v_add_f32_dpp v62, v62, v62 row_half_mirror row_mask:0xf bank_mask:0xf
	v_add_f32_dpp v63, v63, v63 row_half_mirror row_mask:0xf bank_mask:0xf
	v_add_f32_dpp v64, v64, v64 row_half_mirror row_mask:0xf bank_mask:0xf
	v_add_f32_dpp v56, v56, v56 row_mirror row_mask:0xf bank_mask:0xf
	v_add_f32_dpp v57, v57, v57 row_mirror row_mask:0xf bank_mask:0xf
	v_add_f32_dpp v58, v58, v58 row_mirror row_mask:0xf bank_mask:0xf
	v_add_f32_dpp v59, v59, v59 row_mirror row_mask:0xf bank_mask:0xf
	v_add_f32_dpp v60, v60, v60 row_mirror row_mask:0xf bank_mask:0xf
	v_add_f32_dpp v61, v61, v61 row_mirror row_mask:0xf bank_mask:0xf
	v_add_f32_dpp v62, v62, v62 row_mirror row_mask:0xf bank_mask:0xf
	v_add_f32_dpp v63, v63, v63 row_mirror row_mask:0xf bank_mask:0xf
	v_add_f32_dpp v64, v64, v64 row_mirror row_mask:0xf bank_mask:0xf
	v_add_f32_dpp v56, v56, v56 row_bcast:15 row_mask:0xa bank_mask:0xf
	v_add_f32_dpp v57, v57, v57 row_bcast:15 row_mask:0xa bank_mask:0xf
	v_add_f32_dpp v58, v58, v58 row_bcast:15 row_mask:0xa bank_mask:0xf
	v_add_f32_dpp v59, v59, v59 row_bcast:15 row_mask:0xa bank_mask:0xf
	v_add_f32_dpp v60, v60, v60 row_bcast:15 row_mask:0xa bank_mask:0xf
	v_add_f32_dpp v61, v61, v61 row_bcast:15 row_mask:0xa bank_mask:0xf
	v_add_f32_dpp v62, v62, v62 row_bcast:15 row_mask:0xa bank_mask:0xf
	v_add_f32_dpp v63, v63, v63 row_bcast:15 row_mask:0xa bank_mask:0xf
	v_add_f32_dpp v64, v64, v64 row_bcast:15 row_mask:0xa bank_mask:0xf
	v_add_f32_dpp v56, v56, v56 row_bcast:31 row_mask:0xc bank_mask:0xf
	v_add_f32_dpp v57, v57, v57 row_bcast:31 row_mask:0xc bank_mask:0xf
	v_add_f32_dpp v58, v58, v58 row_bcast:31 row_mask:0xc bank_mask:0xf
	v_add_f32_dpp v59, v59, v59 row_bcast:31 row_mask:0xc bank_mask:0xf
	v_add_f32_dpp v60, v60, v60 row_bcast:31 row_mask:0xc bank_mask:0xf
	v_add_f32_dpp v61, v61, v61 row_bcast:31 row_mask:0xc bank_mask:0xf
	v_add_f32_dpp v62, v62, v62 row_bcast:31 row_mask:0xc bank_mask:0xf
	v_add_f32_dpp v63, v63, v63 row_bcast:31 row_mask:0xc bank_mask:0xf
	v_add_f32_dpp v64, v64, v64 row_bcast:31 row_mask:0xc bank_mask:0xf
	s_nop 1
	v_readlane_b32 s6, v56, 63
	v_readlane_b32 s52, v57, 63
	v_readlane_b32 s53, v58, 63
	v_mov_b32_e32 v56, s6
	v_readlane_b32 s6, v59, 63
	v_mov_b32_e32 v57, s52
	v_readlane_b32 s52, v60, 63
	v_mov_b32_e32 v58, s53
	v_readlane_b32 s53, v61, 63
	v_mov_b32_e32 v59, s6
	v_readlane_b32 s6, v62, 63
	v_mov_b32_e32 v60, s52
	v_readlane_b32 s52, v63, 63
	v_mov_b32_e32 v61, s53
	v_readlane_b32 s53, v64, 63
	v_mov_b32_e32 v62, s6
	v_mov_b32_e32 v63, s52
	v_mov_b32_e32 v64, s53
	v_fmamk_f32 v56, v56, 0x3b800000, v196
	v_fmamk_f32 v57, v57, 0x3b800000, v196
	v_fmamk_f32 v58, v58, 0x3b800000, v196
	v_fmamk_f32 v59, v59, 0x3b800000, v196
	v_fmamk_f32 v60, v60, 0x3b800000, v196
	v_fmamk_f32 v61, v61, 0x3b800000, v196
	v_fmamk_f32 v62, v62, 0x3b800000, v196
	v_fmamk_f32 v63, v63, 0x3b800000, v196
	v_fmamk_f32 v64, v64, 0x3b800000, v196
	v_cmp_gt_f32_e32 vcc, s7, v56
	v_cmp_gt_f32_e64 s[4:5], s7, v57
	v_mul_f32_e32 v65, 0x4b800000, v56
	v_mul_f32_e32 v66, 0x4b800000, v57
	v_cndmask_b32_e32 v56, v56, v65, vcc
	v_cndmask_b32_e64 v57, v57, v66, s[4:5]
	v_rsq_f32_e32 v56, v56
	v_rsq_f32_e32 v57, v57
	v_mul_f32_e32 v65, 0x45800000, v56
	v_mul_f32_e32 v66, 0x45800000, v57
	v_cndmask_b32_e32 v56, v56, v65, vcc
	v_cndmask_b32_e64 v57, v57, v66, s[4:5]
	v_cmp_gt_f32_e32 vcc, s7, v58
	v_cmp_gt_f32_e64 s[4:5], s7, v59
	v_mul_f32_e32 v67, 0x4b800000, v58
	v_mul_f32_e32 v68, 0x4b800000, v59
	v_cndmask_b32_e32 v58, v58, v67, vcc
	v_cndmask_b32_e64 v59, v59, v68, s[4:5]
	v_rsq_f32_e32 v58, v58
	v_rsq_f32_e32 v59, v59
	v_mul_f32_e32 v67, 0x45800000, v58
	v_mul_f32_e32 v68, 0x45800000, v59
	v_cndmask_b32_e32 v58, v58, v67, vcc
	v_cndmask_b32_e64 v59, v59, v68, s[4:5]
	v_cmp_gt_f32_e32 vcc, s7, v60
	v_cmp_gt_f32_e64 s[4:5], s7, v61
	v_mul_f32_e32 v69, 0x4b800000, v60
	v_mul_f32_e32 v70, 0x4b800000, v61
	v_cndmask_b32_e32 v60, v60, v69, vcc
	v_cndmask_b32_e64 v61, v61, v70, s[4:5]
	v_rsq_f32_e32 v60, v60
	v_rsq_f32_e32 v61, v61
	v_mul_f32_e32 v69, 0x45800000, v60
	v_mul_f32_e32 v70, 0x45800000, v61
	v_cndmask_b32_e32 v60, v60, v69, vcc
	v_cndmask_b32_e64 v61, v61, v70, s[4:5]
	v_cmp_gt_f32_e32 vcc, s7, v62
	v_cmp_gt_f32_e64 s[4:5], s7, v63
	v_mul_f32_e32 v71, 0x4b800000, v62
	v_mul_f32_e32 v72, 0x4b800000, v63
	v_cndmask_b32_e32 v62, v62, v71, vcc
	v_cndmask_b32_e64 v63, v63, v72, s[4:5]
	v_rsq_f32_e32 v62, v62
	v_rsq_f32_e32 v63, v63
	v_mul_f32_e32 v71, 0x45800000, v62
	v_mul_f32_e32 v72, 0x45800000, v63
	v_cndmask_b32_e32 v62, v62, v71, vcc
	v_cndmask_b32_e64 v63, v63, v72, s[4:5]
	v_cmp_gt_f32_e32 vcc, s7, v64
	v_mul_f32_e32 v73, 0x4b800000, v64
	s_nop 1
	v_cndmask_b32_e32 v64, v64, v73, vcc
	v_rsq_f32_e32 v64, v64
	s_nop 0
	v_mul_f32_e32 v73, 0x45800000, v64
	v_cndmask_b32_e32 v64, v64, v73, vcc
	v_mul_f32_e32 v20, v20, v56
	v_mul_f32_e32 v21, v21, v56
	v_mul_f32_e32 v22, v22, v56
	v_mul_f32_e32 v23, v23, v56
	v_mul_f32_e32 v20, v0, v20
	v_mul_f32_e32 v21, v1, v21
	v_mul_f32_e32 v22, v2, v22
	v_mul_f32_e32 v23, v3, v23
	v_cvt_pk_bf16_f32 v20, v20, v21
	v_cvt_pk_bf16_f32 v21, v22, v23
	v_mul_f32_e32 v24, v24, v57
	v_mul_f32_e32 v25, v25, v57
	v_mul_f32_e32 v26, v26, v57
	v_mul_f32_e32 v27, v27, v57
	v_mul_f32_e32 v24, v0, v24
	v_mul_f32_e32 v25, v1, v25
	v_mul_f32_e32 v26, v2, v26
	v_mul_f32_e32 v27, v3, v27
	v_cvt_pk_bf16_f32 v24, v24, v25
	v_cvt_pk_bf16_f32 v25, v26, v27
	v_mul_f32_e32 v28, v28, v58
	v_mul_f32_e32 v29, v29, v58
	v_mul_f32_e32 v30, v30, v58
	v_mul_f32_e32 v31, v31, v58
	v_mul_f32_e32 v28, v0, v28
	v_mul_f32_e32 v29, v1, v29
	v_mul_f32_e32 v30, v2, v30
	v_mul_f32_e32 v31, v3, v31
	v_cvt_pk_bf16_f32 v28, v28, v29
	v_cvt_pk_bf16_f32 v29, v30, v31
	v_mul_f32_e32 v32, v32, v59
	v_mul_f32_e32 v33, v33, v59
	v_mul_f32_e32 v34, v34, v59
	v_mul_f32_e32 v35, v35, v59
	v_mul_f32_e32 v32, v0, v32
	v_mul_f32_e32 v33, v1, v33
	v_mul_f32_e32 v34, v2, v34
	v_mul_f32_e32 v35, v3, v35
	v_cvt_pk_bf16_f32 v32, v32, v33
	v_cvt_pk_bf16_f32 v33, v34, v35
	v_mul_f32_e32 v36, v36, v60
	v_mul_f32_e32 v37, v37, v60
	v_mul_f32_e32 v38, v38, v60
	v_mul_f32_e32 v39, v39, v60
	v_mul_f32_e32 v36, v0, v36
	v_mul_f32_e32 v37, v1, v37
	v_mul_f32_e32 v38, v2, v38
	v_mul_f32_e32 v39, v3, v39
	v_cvt_pk_bf16_f32 v36, v36, v37
	v_cvt_pk_bf16_f32 v37, v38, v39
	v_mul_f32_e32 v40, v40, v61
	v_mul_f32_e32 v41, v41, v61
	v_mul_f32_e32 v42, v42, v61
	v_mul_f32_e32 v43, v43, v61
	v_mul_f32_e32 v40, v0, v40
	v_mul_f32_e32 v41, v1, v41
	v_mul_f32_e32 v42, v2, v42
	v_mul_f32_e32 v43, v3, v43
	v_cvt_pk_bf16_f32 v40, v40, v41
	v_cvt_pk_bf16_f32 v41, v42, v43
	v_mul_f32_e32 v44, v44, v62
	v_mul_f32_e32 v45, v45, v62
	v_mul_f32_e32 v46, v46, v62
	v_mul_f32_e32 v47, v47, v62
	v_mul_f32_e32 v44, v0, v44
	v_mul_f32_e32 v45, v1, v45
	v_mul_f32_e32 v46, v2, v46
	v_mul_f32_e32 v47, v3, v47
	v_cvt_pk_bf16_f32 v44, v44, v45
	v_cvt_pk_bf16_f32 v45, v46, v47
	v_mul_f32_e32 v48, v48, v63
	v_mul_f32_e32 v49, v49, v63
	v_mul_f32_e32 v50, v50, v63
	v_mul_f32_e32 v51, v51, v63
	v_mul_f32_e32 v48, v0, v48
	v_mul_f32_e32 v49, v1, v49
	v_mul_f32_e32 v50, v2, v50
	v_mul_f32_e32 v51, v3, v51
	v_cvt_pk_bf16_f32 v48, v48, v49
	v_cvt_pk_bf16_f32 v49, v50, v51
	v_mul_f32_e32 v52, v52, v64
	v_mul_f32_e32 v53, v53, v64
	v_mul_f32_e32 v54, v54, v64
	v_mul_f32_e32 v55, v55, v64
	v_mul_f32_e32 v52, v0, v52
	v_mul_f32_e32 v53, v1, v53
	v_mul_f32_e32 v54, v2, v54
	v_mul_f32_e32 v55, v3, v55
	v_cvt_pk_bf16_f32 v52, v52, v53
	v_cvt_pk_bf16_f32 v53, v54, v55
	v_lshlrev_b64 v[16:17], 9, v[4:5]
	v_lshl_add_u64 v[16:17], v[8:9], 0, v[16:17]
	s_mov_b32 s44, 0x100000
	v_readfirstlane_b32 s6, v4
	s_add_i32 s6, s6, 0x4000
	s_min_u32 s6, s6, s8
	s_lshl_b32 s52, s6, 9
	s_mov_b32 s53, 0
	global_store_dwordx2 v[16:17], v[20:21], off
	v_lshl_add_u64 v[18:19], v[16:17], 0, s[44:45]
	global_store_dwordx2 v[18:19], v[24:25], off
	v_lshl_add_u64 v[16:17], v[18:19], 0, s[44:45]
	global_store_dwordx2 v[16:17], v[28:29], off
	v_lshl_add_u64 v[18:19], v[16:17], 0, s[44:45]
	global_store_dwordx2 v[18:19], v[32:33], off
	v_lshl_add_u64 v[16:17], v[18:19], 0, s[44:45]
	global_store_dwordx2 v[16:17], v[36:37], off
	v_lshl_add_u64 v[18:19], v[16:17], 0, s[44:45]
	global_store_dwordx2 v[18:19], v[40:41], off
	v_lshl_add_u64 v[16:17], v[18:19], 0, s[44:45]
	global_store_dwordx2 v[16:17], v[44:45], off
	v_lshl_add_u64 v[18:19], v[16:17], 0, s[44:45]
	global_store_dwordx2 v[18:19], v[48:49], off
	v_lshl_add_u64 v[16:17], v[8:9], 0, s[52:53]
	global_store_dwordx2 v[16:17], v[52:53], off
	s_branch .LBB0_295

.LBB0_1086:
	s_lshl_b32 s0, s29, 14
	s_ashr_i32 s1, s0, 31
	v_lshl_add_u64 v[52:53], s[0:1], 1, v[72:73]
	s_mov_b64 s[0:1], 0x2740000
	s_waitcnt vmcnt(0)
	v_lshl_add_u64 v[4:5], v[52:53], 0, s[0:1]
	v_lshlrev_b64 v[54:55], 1, v[80:81]
	v_lshl_add_u64 v[0:1], v[4:5], 0, v[54:55]
	global_load_dwordx4 v[0:3], v[0:1], off
	v_lshlrev_b64 v[56:57], 1, v[82:83]
	v_lshlrev_b64 v[58:59], 1, v[84:85]
	v_lshlrev_b64 v[60:61], 1, v[86:87]
	v_lshlrev_b64 v[62:63], 1, v[88:89]
	v_lshlrev_b64 v[64:65], 1, v[90:91]
	v_lshlrev_b64 v[66:67], 1, v[92:93]
	v_lshlrev_b64 v[68:69], 1, v[94:95]
	s_ashr_i32 s23, s22, 31
	v_lshl_add_u64 v[70:71], s[22:23], 2, v[78:79]
	s_mov_b64 s[0:1], 0x2790000
	v_lshl_add_u64 v[8:9], v[4:5], 0, v[56:57]
	global_load_dwordx4 v[8:11], v[8:9], off
	v_lshl_add_u64 v[12:13], v[4:5], 0, v[58:59]
	global_load_dwordx4 v[12:15], v[12:13], off
	v_lshl_add_u64 v[16:17], v[4:5], 0, v[60:61]
	global_load_dwordx4 v[16:19], v[16:17], off
	v_lshl_add_u64 v[20:21], v[4:5], 0, v[62:63]
	global_load_dwordx4 v[20:23], v[20:21], off
	v_lshl_add_u64 v[24:25], v[4:5], 0, v[64:65]
	global_load_dwordx4 v[24:27], v[24:25], off
	v_lshl_add_u64 v[28:29], v[4:5], 0, v[66:67]
	global_load_dwordx4 v[28:31], v[28:29], off
	v_lshl_add_u64 v[32:33], v[4:5], 0, v[68:69]
	global_load_dwordx4 v[32:35], v[32:33], off
	s_waitcnt vmcnt(7)
	ds_write_b128 v120, v[0:3] offset:32768
	s_waitcnt vmcnt(6)
	ds_write_b128 v121, v[8:11] offset:32768
	s_waitcnt vmcnt(5)
	ds_write_b128 v122, v[12:15] offset:32768
	s_waitcnt vmcnt(4)
	ds_write_b128 v123, v[16:19] offset:32768
	s_waitcnt vmcnt(3)
	ds_write_b128 v124, v[20:23] offset:32768
	s_waitcnt vmcnt(2)
	ds_write_b128 v125, v[24:27] offset:32768
	s_waitcnt vmcnt(1)
	ds_write_b128 v126, v[28:31] offset:32768
	s_waitcnt vmcnt(0)
	ds_write_b128 v127, v[32:35] offset:32768
	s_waitcnt lgkmcnt(0)
	s_barrier
	ds_read_b128 v[0:3], v116
	ds_read_b128 v[4:7], v116 offset:2048
	ds_read_b128 v[8:11], v116 offset:4096
	ds_read_b128 v[12:15], v116 offset:6144
	ds_read_b128 v[16:19], v117 offset:32768
	ds_read_b128 v[20:23], v117 offset:34816
	ds_read_b128 v[24:27], v117 offset:36864
	ds_read_b128 v[28:31], v117 offset:38912
	s_waitcnt lgkmcnt(3)
	v_mfma_f32_16x16x32_bf16 v[32:35], v[16:19], v[0:3], 0
	s_waitcnt lgkmcnt(2)
	v_mfma_f32_16x16x32_bf16 v[36:39], v[20:23], v[0:3], 0
	s_waitcnt lgkmcnt(1)
	v_mfma_f32_16x16x32_bf16 v[40:43], v[24:27], v[0:3], 0
	s_waitcnt lgkmcnt(0)
	v_mfma_f32_16x16x32_bf16 v[0:3], v[28:31], v[0:3], 0
	v_mfma_f32_16x16x32_bf16 v[44:47], v[16:19], v[4:7], 0
	v_mfma_f32_16x16x32_bf16 v[48:51], v[20:23], v[4:7], 0
	v_mfma_f32_16x16x32_bf16 v[96:99], v[24:27], v[4:7], 0
	v_mfma_f32_16x16x32_bf16 v[4:7], v[28:31], v[4:7], 0
	v_mfma_f32_16x16x32_bf16 v[100:103], v[16:19], v[8:11], 0
	v_mfma_f32_16x16x32_bf16 v[128:131], v[20:23], v[8:11], 0
	v_mfma_f32_16x16x32_bf16 v[132:135], v[24:27], v[8:11], 0
	v_mfma_f32_16x16x32_bf16 v[8:11], v[28:31], v[8:11], 0
	v_mfma_f32_16x16x32_bf16 v[16:19], v[16:19], v[12:15], 0
	v_mfma_f32_16x16x32_bf16 v[20:23], v[20:23], v[12:15], 0
	v_mfma_f32_16x16x32_bf16 v[24:27], v[24:27], v[12:15], 0
	v_mfma_f32_16x16x32_bf16 v[12:15], v[28:31], v[12:15], 0
	ds_read_b128 v[28:31], v118
	ds_read_b128 v[136:139], v118 offset:2048
	ds_read_b128 v[140:143], v118 offset:4096
	ds_read_b128 v[144:147], v118 offset:6144
	ds_read_b128 v[148:151], v119 offset:32768
	ds_read_b128 v[152:155], v119 offset:34816
	ds_read_b128 v[156:159], v119 offset:36864
	ds_read_b128 v[160:163], v119 offset:38912
	s_waitcnt lgkmcnt(3)
	v_mfma_f32_16x16x32_bf16 v[32:35], v[148:151], v[28:31], v[32:35]
	s_waitcnt lgkmcnt(2)
	v_mfma_f32_16x16x32_bf16 v[36:39], v[152:155], v[28:31], v[36:39]
	s_waitcnt lgkmcnt(1)
	v_mfma_f32_16x16x32_bf16 v[40:43], v[156:159], v[28:31], v[40:43]
	s_waitcnt lgkmcnt(0)
	v_mfma_f32_16x16x32_bf16 v[0:3], v[160:163], v[28:31], v[0:3]
	v_mfma_f32_16x16x32_bf16 v[28:31], v[148:151], v[136:139], v[44:47]
	v_mfma_f32_16x16x32_bf16 v[44:47], v[152:155], v[136:139], v[48:51]
	v_mfma_f32_16x16x32_bf16 v[48:51], v[156:159], v[136:139], v[96:99]
	v_mfma_f32_16x16x32_bf16 v[4:7], v[160:163], v[136:139], v[4:7]
	v_mfma_f32_16x16x32_bf16 v[96:99], v[148:151], v[140:143], v[100:103]
	v_mfma_f32_16x16x32_bf16 v[100:103], v[152:155], v[140:143], v[128:131]
	v_mfma_f32_16x16x32_bf16 v[128:131], v[156:159], v[140:143], v[132:135]
	v_mfma_f32_16x16x32_bf16 v[8:11], v[160:163], v[140:143], v[8:11]
	v_mfma_f32_16x16x32_bf16 v[16:19], v[148:151], v[144:147], v[16:19]
	v_mfma_f32_16x16x32_bf16 v[20:23], v[152:155], v[144:147], v[20:23]
	v_mfma_f32_16x16x32_bf16 v[24:27], v[156:159], v[144:147], v[24:27]
	v_mfma_f32_16x16x32_bf16 v[12:15], v[160:163], v[144:147], v[12:15]
	ds_read_b128 v[132:135], v116 offset:16384
	ds_read_b128 v[136:139], v116 offset:18432
	ds_read_b128 v[140:143], v116 offset:20480
	ds_read_b128 v[144:147], v116 offset:22528
	ds_read_b128 v[148:151], v117 offset:49152
	ds_read_b128 v[152:155], v117 offset:51200
	ds_read_b128 v[156:159], v117 offset:53248
	ds_read_b128 v[160:163], v117 offset:55296
	s_waitcnt lgkmcnt(3)
	v_mfma_f32_16x16x32_bf16 v[32:35], v[148:151], v[132:135], v[32:35]
	s_waitcnt lgkmcnt(2)
	v_mfma_f32_16x16x32_bf16 v[36:39], v[152:155], v[132:135], v[36:39]
	s_waitcnt lgkmcnt(1)
	v_mfma_f32_16x16x32_bf16 v[40:43], v[156:159], v[132:135], v[40:43]
	s_waitcnt lgkmcnt(0)
	v_mfma_f32_16x16x32_bf16 v[0:3], v[160:163], v[132:135], v[0:3]
	v_mfma_f32_16x16x32_bf16 v[132:135], v[148:151], v[136:139], v[28:31]
	v_mfma_f32_16x16x32_bf16 v[164:167], v[152:155], v[136:139], v[44:47]
	v_mfma_f32_16x16x32_bf16 v[48:51], v[156:159], v[136:139], v[48:51]
	v_mfma_f32_16x16x32_bf16 v[4:7], v[160:163], v[136:139], v[4:7]
	v_mfma_f32_16x16x32_bf16 v[96:99], v[148:151], v[140:143], v[96:99]
	v_mfma_f32_16x16x32_bf16 v[100:103], v[152:155], v[140:143], v[100:103]
	v_mfma_f32_16x16x32_bf16 v[128:131], v[156:159], v[140:143], v[128:131]
	v_mfma_f32_16x16x32_bf16 v[136:139], v[160:163], v[140:143], v[8:11]
	v_mfma_f32_16x16x32_bf16 v[16:19], v[148:151], v[144:147], v[16:19]
	v_mfma_f32_16x16x32_bf16 v[140:143], v[152:155], v[144:147], v[20:23]
	v_mfma_f32_16x16x32_bf16 v[148:151], v[156:159], v[144:147], v[24:27]
	v_mfma_f32_16x16x32_bf16 v[144:147], v[160:163], v[144:147], v[12:15]
	ds_read_b128 v[8:11], v118 offset:16384
	ds_read_b128 v[20:23], v118 offset:18432
	ds_read_b128 v[152:155], v118 offset:20480
	ds_read_b128 v[156:159], v118 offset:22528
	ds_read_b128 v[160:163], v119 offset:49152
	ds_read_b128 v[168:171], v119 offset:51200
	ds_read_b128 v[172:175], v119 offset:53248
	ds_read_b128 v[178:181], v119 offset:55296
	s_waitcnt lgkmcnt(3)
	v_mfma_f32_16x16x32_bf16 v[182:185], v[160:163], v[8:11], v[32:35]
	s_waitcnt lgkmcnt(2)
	v_mfma_f32_16x16x32_bf16 v[44:47], v[168:171], v[8:11], v[36:39]
	s_waitcnt lgkmcnt(1)
	v_mfma_f32_16x16x32_bf16 v[28:31], v[172:175], v[8:11], v[40:43]
	s_waitcnt lgkmcnt(0)
	v_mfma_f32_16x16x32_bf16 v[12:15], v[178:181], v[8:11], v[0:3]
	v_mfma_f32_16x16x32_bf16 v[8:11], v[178:181], v[20:23], v[4:7]
	v_mfma_f32_16x16x32_bf16 v[4:7], v[178:181], v[152:155], v[136:139]
	s_nop 2
	global_load_dwordx4 v[136:139], v[70:71], off
	v_mfma_f32_16x16x32_bf16 v[24:27], v[172:175], v[20:23], v[48:51]
	v_mfma_f32_16x16x32_bf16 v[48:51], v[160:163], v[152:155], v[96:99]
	v_mfma_f32_16x16x32_bf16 v[132:135], v[160:163], v[20:23], v[132:135]
	s_waitcnt vmcnt(0)
	s_nop 0
	v_add_f32_e32 v97, v183, v137
	s_nop 3
	v_add_f32_e32 v48, v48, v136
	v_add_f32_e32 v49, v49, v137
	v_mul_f32_e32 v48, 0xbfb8aa3b, v48
	v_mul_f32_e32 v49, 0xbfb8aa3b, v49
	v_exp_f32_e32 v48, v48
	v_exp_f32_e32 v49, v49
	v_mfma_f32_16x16x32_bf16 v[40:43], v[168:171], v[20:23], v[164:167]
	v_add_f32_e32 v96, v182, v136
	v_add_f32_e32 v48, 1.0, v48
	v_add_f32_e32 v49, 1.0, v49
	v_rcp_f32_e32 v48, v48
	v_rcp_f32_e32 v49, v49
	s_nop 1
	v_cvt_pk_bf16_f32 v99, v48, v49
	v_add_f32_e32 v48, v50, v138
	v_add_f32_e32 v49, v51, v139
	v_mul_f32_e32 v48, 0xbfb8aa3b, v48
	v_mul_f32_e32 v49, 0xbfb8aa3b, v49
	v_exp_f32_e32 v48, v48
	v_exp_f32_e32 v49, v49
	v_mfma_f32_16x16x32_bf16 v[20:23], v[172:175], v[152:155], v[128:131]
	v_mul_f32_e32 v97, 0xbfb8aa3b, v97
	v_add_f32_e32 v48, 1.0, v48
	v_add_f32_e32 v49, 1.0, v49
	v_mfma_f32_16x16x32_bf16 v[128:131], v[160:163], v[156:159], v[16:19]
	v_rcp_f32_e32 v48, v48
	v_rcp_f32_e32 v49, v49
	s_nop 1
	v_cvt_pk_bf16_f32 v98, v48, v49
	v_mfma_f32_16x16x32_bf16 v[36:39], v[168:171], v[152:155], v[100:103]
	v_mul_f32_e32 v96, 0xbfb8aa3b, v96
	s_nop 3
	v_add_f32_e32 v48, v128, v136
	v_add_f32_e32 v49, v129, v137
	v_mul_f32_e32 v48, 0xbfb8aa3b, v48
	v_mul_f32_e32 v49, 0xbfb8aa3b, v49
	v_exp_f32_e32 v48, v48
	v_exp_f32_e32 v49, v49
	v_mfma_f32_16x16x32_bf16 v[32:35], v[168:171], v[156:159], v[140:143]
	v_exp_f32_e32 v97, v97
	v_add_f32_e32 v48, 1.0, v48
	v_add_f32_e32 v49, 1.0, v49
	v_rcp_f32_e32 v48, v48
	v_rcp_f32_e32 v49, v49
	s_nop 1
	v_cvt_pk_bf16_f32 v102, v48, v49
	v_add_f32_e32 v48, v130, v138
	v_add_f32_e32 v49, v131, v139
	v_mul_f32_e32 v48, 0xbfb8aa3b, v48
	v_mul_f32_e32 v49, 0xbfb8aa3b, v49
	v_exp_f32_e32 v48, v48
	v_exp_f32_e32 v49, v49
	v_mfma_f32_16x16x32_bf16 v[0:3], v[178:181], v[156:159], v[144:147]
	v_exp_f32_e32 v96, v96
	v_add_f32_e32 v48, 1.0, v48
	v_add_f32_e32 v49, 1.0, v49
	v_rcp_f32_e32 v48, v48
	v_rcp_f32_e32 v49, v49
	s_nop 1
	v_cvt_pk_bf16_f32 v101, v48, v49
	global_load_dwordx4 v[48:51], v[70:71], off offset:64
	v_mfma_f32_16x16x32_bf16 v[16:19], v[172:175], v[156:159], v[148:151]
	v_add_f32_e32 v97, 1.0, v97
	v_add_f32_e32 v96, 1.0, v96
	v_rcp_f32_e32 v97, v97
	v_rcp_f32_e32 v96, v96
	s_nop 1
	v_cvt_pk_bf16_f32 v152, v96, v97
	v_add_f32_e32 v97, v185, v139
	v_add_f32_e32 v96, v184, v138
	v_mul_f32_e32 v97, 0xbfb8aa3b, v97
	v_mul_f32_e32 v96, 0xbfb8aa3b, v96
	v_exp_f32_e32 v97, v97
	v_exp_f32_e32 v96, v96
	v_or_b32_e32 v100, s22, v74
	v_add_f32_e32 v97, 1.0, v97
	v_add_f32_e32 v96, 1.0, v96
	v_rcp_f32_e32 v97, v97
	v_rcp_f32_e32 v96, v96
	s_nop 1
	v_cvt_pk_bf16_f32 v105, v96, v97
	v_add_f32_e32 v97, v133, v137
	v_add_f32_e32 v96, v132, v136
	v_mul_f32_e32 v97, 0xbfb8aa3b, v97
	v_mul_f32_e32 v96, 0xbfb8aa3b, v96
	v_exp_f32_e32 v97, v97
	v_exp_f32_e32 v96, v96
	v_add_f32_e32 v97, 1.0, v97
	v_add_f32_e32 v96, 1.0, v96
	v_rcp_f32_e32 v97, v97
	v_rcp_f32_e32 v96, v96
	s_nop 1
	v_cvt_pk_bf16_f32 v104, v96, v97
	v_add_f32_e32 v97, v135, v139
	v_add_f32_e32 v96, v134, v138
	v_mul_f32_e32 v96, 0xbfb8aa3b, v96
	v_exp_f32_e32 v96, v96
	v_mul_f32_e32 v97, 0xbfb8aa3b, v97
	v_exp_f32_e32 v97, v97
	v_add_f32_e32 v96, 1.0, v96
	v_rcp_f32_e32 v96, v96
	v_add_f32_e32 v97, 1.0, v97
	v_rcp_f32_e32 v97, v97
	s_nop 1
	v_cvt_pk_bf16_f32 v103, v96, v97
	s_waitcnt vmcnt(0)
	v_add_f32_e32 v32, v32, v48
	v_add_f32_e32 v33, v33, v49
	v_mul_f32_e32 v32, 0xbfb8aa3b, v32
	v_mul_f32_e32 v33, 0xbfb8aa3b, v33
	v_exp_f32_e32 v32, v32
	v_exp_f32_e32 v33, v33
	v_add_f32_e32 v44, v44, v48
	v_add_f32_e32 v45, v45, v49
	v_add_f32_e32 v32, 1.0, v32
	v_add_f32_e32 v33, 1.0, v33
	v_rcp_f32_e32 v32, v32
	v_rcp_f32_e32 v33, v33
	s_nop 1
	v_cvt_pk_bf16_f32 v145, v32, v33
	v_add_f32_e32 v32, v34, v50
	v_add_f32_e32 v33, v35, v51
	v_mul_f32_e32 v32, 0xbfb8aa3b, v32
	v_mul_f32_e32 v33, 0xbfb8aa3b, v33
	v_exp_f32_e32 v32, v32
	v_exp_f32_e32 v33, v33
	v_add_f32_e32 v40, v40, v48
	v_add_f32_e32 v41, v41, v49
	v_add_f32_e32 v32, 1.0, v32
	v_add_f32_e32 v33, 1.0, v33
	v_rcp_f32_e32 v32, v32
	v_rcp_f32_e32 v33, v33
	s_nop 1
	v_cvt_pk_bf16_f32 v144, v32, v33
	global_load_dwordx4 v[32:35], v[70:71], off offset:128
	v_add_f32_e32 v36, v36, v48
	v_add_f32_e32 v37, v37, v49
	v_mul_f32_e32 v44, 0xbfb8aa3b, v44
	v_mul_f32_e32 v45, 0xbfb8aa3b, v45
	v_mul_f32_e32 v40, 0xbfb8aa3b, v40
	v_mul_f32_e32 v41, 0xbfb8aa3b, v41
	v_mul_f32_e32 v36, 0xbfb8aa3b, v36
	v_mul_f32_e32 v37, 0xbfb8aa3b, v37
	v_exp_f32_e32 v44, v44
	v_exp_f32_e32 v45, v45
	v_exp_f32_e32 v40, v40
	v_exp_f32_e32 v41, v41
	v_exp_f32_e32 v36, v36
	v_exp_f32_e32 v37, v37
	v_add_f32_e32 v44, 1.0, v44
	v_add_f32_e32 v45, 1.0, v45
	v_add_f32_e32 v40, 1.0, v40
	v_add_f32_e32 v41, 1.0, v41
	v_add_f32_e32 v36, 1.0, v36
	v_add_f32_e32 v37, 1.0, v37
	v_rcp_f32_e32 v44, v44
	v_rcp_f32_e32 v45, v45
	v_rcp_f32_e32 v40, v40
	v_rcp_f32_e32 v41, v41
	v_rcp_f32_e32 v36, v36
	v_rcp_f32_e32 v37, v37
	s_nop 1
	v_cvt_pk_bf16_f32 v151, v44, v45
	v_add_f32_e32 v44, v46, v50
	v_add_f32_e32 v45, v47, v51
	s_nop 1
	v_cvt_pk_bf16_f32 v149, v40, v41
	v_add_f32_e32 v40, v42, v50
	v_add_f32_e32 v41, v43, v51
	s_nop 1
	v_cvt_pk_bf16_f32 v147, v36, v37
	v_add_f32_e32 v36, v38, v50
	v_add_f32_e32 v37, v39, v51
	v_mul_f32_e32 v44, 0xbfb8aa3b, v44
	v_mul_f32_e32 v45, 0xbfb8aa3b, v45
	v_mul_f32_e32 v40, 0xbfb8aa3b, v40
	v_mul_f32_e32 v41, 0xbfb8aa3b, v41
	v_mul_f32_e32 v36, 0xbfb8aa3b, v36
	v_mul_f32_e32 v37, 0xbfb8aa3b, v37
	v_exp_f32_e32 v44, v44
	v_exp_f32_e32 v45, v45
	v_exp_f32_e32 v40, v40
	v_exp_f32_e32 v41, v41
	v_exp_f32_e32 v36, v36
	v_exp_f32_e32 v37, v37
	v_add_f32_e32 v44, 1.0, v44
	v_add_f32_e32 v45, 1.0, v45
	v_add_f32_e32 v40, 1.0, v40
	v_add_f32_e32 v41, 1.0, v41
	v_add_f32_e32 v36, 1.0, v36
	v_add_f32_e32 v37, 1.0, v37
	v_rcp_f32_e32 v44, v44
	v_rcp_f32_e32 v45, v45
	v_rcp_f32_e32 v40, v40
	v_rcp_f32_e32 v41, v41
	v_rcp_f32_e32 v36, v36
	v_rcp_f32_e32 v37, v37
	s_nop 1
	v_cvt_pk_bf16_f32 v150, v44, v45
	s_nop 1
	v_cvt_pk_bf16_f32 v148, v40, v41
	s_nop 1
	v_cvt_pk_bf16_f32 v146, v36, v37
	s_waitcnt vmcnt(0)
	v_add_f32_e32 v16, v16, v32
	v_add_f32_e32 v17, v17, v33
	v_mul_f32_e32 v16, 0xbfb8aa3b, v16
	v_mul_f32_e32 v17, 0xbfb8aa3b, v17
	v_exp_f32_e32 v16, v16
	v_exp_f32_e32 v17, v17
	v_add_f32_e32 v28, v28, v32
	v_add_f32_e32 v29, v29, v33
	v_add_f32_e32 v16, 1.0, v16
	v_add_f32_e32 v17, 1.0, v17
	v_rcp_f32_e32 v16, v16
	v_rcp_f32_e32 v17, v17
	s_nop 1
	v_cvt_pk_bf16_f32 v137, v16, v17
	v_add_f32_e32 v16, v18, v34
	v_add_f32_e32 v17, v19, v35
	v_mul_f32_e32 v16, 0xbfb8aa3b, v16
	v_mul_f32_e32 v17, 0xbfb8aa3b, v17
	v_exp_f32_e32 v16, v16
	v_exp_f32_e32 v17, v17
	v_add_f32_e32 v24, v24, v32
	v_add_f32_e32 v25, v25, v33
	v_add_f32_e32 v16, 1.0, v16
	v_add_f32_e32 v17, 1.0, v17
	v_rcp_f32_e32 v16, v16
	v_rcp_f32_e32 v17, v17
	s_nop 1
	v_cvt_pk_bf16_f32 v136, v16, v17
	global_load_dwordx4 v[16:19], v[70:71], off offset:192
	s_barrier
	v_add_f32_e32 v20, v20, v32
	v_add_f32_e32 v21, v21, v33
	v_mul_f32_e32 v28, 0xbfb8aa3b, v28
	v_mul_f32_e32 v29, 0xbfb8aa3b, v29
	v_mul_f32_e32 v24, 0xbfb8aa3b, v24
	v_mul_f32_e32 v25, 0xbfb8aa3b, v25
	v_mul_f32_e32 v20, 0xbfb8aa3b, v20
	v_mul_f32_e32 v21, 0xbfb8aa3b, v21
	v_exp_f32_e32 v28, v28
	v_exp_f32_e32 v29, v29
	v_exp_f32_e32 v24, v24
	v_exp_f32_e32 v25, v25
	v_exp_f32_e32 v20, v20
	v_exp_f32_e32 v21, v21
	v_add_f32_e32 v28, 1.0, v28
	v_add_f32_e32 v29, 1.0, v29
	v_add_f32_e32 v24, 1.0, v24
	v_add_f32_e32 v25, 1.0, v25
	v_add_f32_e32 v20, 1.0, v20
	v_add_f32_e32 v21, 1.0, v21
	v_rcp_f32_e32 v28, v28
	v_rcp_f32_e32 v29, v29
	v_rcp_f32_e32 v24, v24
	v_rcp_f32_e32 v25, v25
	v_rcp_f32_e32 v20, v20
	v_rcp_f32_e32 v21, v21
	s_nop 1
	v_cvt_pk_bf16_f32 v143, v28, v29
	v_add_f32_e32 v28, v30, v34
	v_add_f32_e32 v29, v31, v35
	s_nop 1
	v_cvt_pk_bf16_f32 v141, v24, v25
	v_add_f32_e32 v24, v26, v34
	v_add_f32_e32 v25, v27, v35
	s_nop 1
	v_cvt_pk_bf16_f32 v139, v20, v21
	v_add_f32_e32 v20, v22, v34
	v_add_f32_e32 v21, v23, v35
	v_mul_f32_e32 v28, 0xbfb8aa3b, v28
	v_mul_f32_e32 v29, 0xbfb8aa3b, v29
	v_mul_f32_e32 v24, 0xbfb8aa3b, v24
	v_mul_f32_e32 v25, 0xbfb8aa3b, v25
	v_mul_f32_e32 v20, 0xbfb8aa3b, v20
	v_mul_f32_e32 v21, 0xbfb8aa3b, v21
	v_exp_f32_e32 v28, v28
	v_exp_f32_e32 v29, v29
	v_exp_f32_e32 v24, v24
	v_exp_f32_e32 v25, v25
	v_exp_f32_e32 v20, v20
	v_exp_f32_e32 v21, v21
	v_add_f32_e32 v28, 1.0, v28
	v_add_f32_e32 v29, 1.0, v29
	v_add_f32_e32 v24, 1.0, v24
	v_add_f32_e32 v25, 1.0, v25
	v_add_f32_e32 v20, 1.0, v20
	v_add_f32_e32 v21, 1.0, v21
	v_rcp_f32_e32 v28, v28
	v_rcp_f32_e32 v29, v29
	v_rcp_f32_e32 v24, v24
	v_rcp_f32_e32 v25, v25
	v_rcp_f32_e32 v20, v20
	v_rcp_f32_e32 v21, v21
	s_nop 1
	v_cvt_pk_bf16_f32 v142, v28, v29
	s_nop 1
	v_cvt_pk_bf16_f32 v140, v24, v25
	s_nop 1
	v_cvt_pk_bf16_f32 v138, v20, v21
	s_waitcnt vmcnt(0)
	v_add_f32_e32 v4, v4, v16
	v_add_f32_e32 v5, v5, v17
	v_mul_f32_e32 v4, 0xbfb8aa3b, v4
	v_mul_f32_e32 v5, 0xbfb8aa3b, v5
	v_add_f32_e32 v0, v0, v16
	v_add_f32_e32 v1, v1, v17
	v_exp_f32_e32 v4, v4
	v_exp_f32_e32 v5, v5
	v_mul_f32_e32 v0, 0xbfb8aa3b, v0
	v_mul_f32_e32 v1, 0xbfb8aa3b, v1
	v_exp_f32_e32 v0, v0
	v_exp_f32_e32 v1, v1
	v_add_f32_e32 v4, 1.0, v4
	v_add_f32_e32 v5, 1.0, v5
	v_rcp_f32_e32 v4, v4
	v_rcp_f32_e32 v5, v5
	v_add_f32_e32 v0, 1.0, v0
	v_add_f32_e32 v1, 1.0, v1
	s_nop 1
	v_cvt_pk_bf16_f32 v131, v4, v5
	v_add_f32_e32 v4, v6, v18
	v_add_f32_e32 v5, v7, v19
	v_rcp_f32_e32 v0, v0
	v_rcp_f32_e32 v1, v1
	v_mul_f32_e32 v4, 0xbfb8aa3b, v4
	v_mul_f32_e32 v5, 0xbfb8aa3b, v5
	s_nop 1
	v_cvt_pk_bf16_f32 v129, v0, v1
	v_add_f32_e32 v0, v2, v18
	v_add_f32_e32 v1, v3, v19
	v_exp_f32_e32 v4, v4
	v_exp_f32_e32 v5, v5
	v_mul_f32_e32 v0, 0xbfb8aa3b, v0
	v_mul_f32_e32 v1, 0xbfb8aa3b, v1
	v_exp_f32_e32 v0, v0
	v_exp_f32_e32 v1, v1
	v_add_f32_e32 v4, 1.0, v4
	v_add_f32_e32 v5, 1.0, v5
	v_rcp_f32_e32 v4, v4
	v_rcp_f32_e32 v5, v5
	v_add_f32_e32 v0, 1.0, v0
	v_add_f32_e32 v1, 1.0, v1
	s_nop 1
	v_cvt_pk_bf16_f32 v130, v4, v5
	v_rcp_f32_e32 v0, v0
	v_rcp_f32_e32 v1, v1
	v_lshl_add_u64 v[4:5], v[52:53], 0, s[0:1]
	s_nop 1
	v_cvt_pk_bf16_f32 v128, v0, v1
	v_lshl_add_u64 v[0:1], v[4:5], 0, v[54:55]
	global_load_dwordx4 v[0:3], v[0:1], off
	v_add_f32_e32 v12, v12, v16
	v_add_f32_e32 v13, v13, v17
	v_add_f32_e32 v8, v8, v16
	v_add_f32_e32 v9, v9, v17
	v_mul_f32_e32 v12, 0xbfb8aa3b, v12
	v_mul_f32_e32 v13, 0xbfb8aa3b, v13
	v_mul_f32_e32 v8, 0xbfb8aa3b, v8
	v_mul_f32_e32 v9, 0xbfb8aa3b, v9
	v_exp_f32_e32 v12, v12
	v_exp_f32_e32 v13, v13
	v_exp_f32_e32 v8, v8
	v_exp_f32_e32 v9, v9
	v_add_f32_e32 v12, 1.0, v12
	v_add_f32_e32 v13, 1.0, v13
	v_add_f32_e32 v8, 1.0, v8
	v_add_f32_e32 v9, 1.0, v9
	v_rcp_f32_e32 v12, v12
	v_rcp_f32_e32 v13, v13
	v_rcp_f32_e32 v8, v8
	v_rcp_f32_e32 v9, v9
	s_nop 1
	v_cvt_pk_bf16_f32 v135, v12, v13
	v_add_f32_e32 v12, v14, v18
	v_add_f32_e32 v13, v15, v19
	s_nop 1
	v_cvt_pk_bf16_f32 v133, v8, v9
	v_add_f32_e32 v8, v10, v18
	v_add_f32_e32 v9, v11, v19
	v_mul_f32_e32 v12, 0xbfb8aa3b, v12
	v_mul_f32_e32 v13, 0xbfb8aa3b, v13
	v_mul_f32_e32 v8, 0xbfb8aa3b, v8
	v_mul_f32_e32 v9, 0xbfb8aa3b, v9
	v_exp_f32_e32 v12, v12
	v_exp_f32_e32 v13, v13
	v_exp_f32_e32 v8, v8
	v_exp_f32_e32 v9, v9
	v_add_f32_e32 v12, 1.0, v12
	v_add_f32_e32 v13, 1.0, v13
	v_add_f32_e32 v8, 1.0, v8
	v_add_f32_e32 v9, 1.0, v9
	v_rcp_f32_e32 v12, v12
	v_rcp_f32_e32 v13, v13
	v_rcp_f32_e32 v8, v8
	v_rcp_f32_e32 v9, v9
	s_nop 1
	v_cvt_pk_bf16_f32 v134, v12, v13
	s_nop 1
	v_cvt_pk_bf16_f32 v132, v8, v9
	s_mov_b32 s0, 0x800000
	v_lshl_add_u64 v[8:9], v[4:5], 0, v[56:57]
	global_load_dwordx4 v[8:11], v[8:9], off
	v_lshl_add_u64 v[12:13], v[4:5], 0, v[58:59]
	global_load_dwordx4 v[12:15], v[12:13], off
	v_lshl_add_u64 v[16:17], v[4:5], 0, v[60:61]
	global_load_dwordx4 v[16:19], v[16:17], off
	v_lshl_add_u64 v[20:21], v[4:5], 0, v[62:63]
	global_load_dwordx4 v[20:23], v[20:21], off
	v_lshl_add_u64 v[24:25], v[4:5], 0, v[64:65]
	global_load_dwordx4 v[24:27], v[24:25], off
	v_lshl_add_u64 v[28:29], v[4:5], 0, v[66:67]
	global_load_dwordx4 v[28:31], v[28:29], off
	v_lshl_add_u64 v[32:33], v[4:5], 0, v[68:69]
	global_load_dwordx4 v[32:35], v[32:33], off
	s_waitcnt vmcnt(7)
	ds_write_b128 v120, v[0:3] offset:32768
	s_waitcnt vmcnt(6)
	ds_write_b128 v121, v[8:11] offset:32768
	s_waitcnt vmcnt(5)
	ds_write_b128 v122, v[12:15] offset:32768
	s_waitcnt vmcnt(4)
	ds_write_b128 v123, v[16:19] offset:32768
	s_waitcnt vmcnt(3)
	ds_write_b128 v124, v[20:23] offset:32768
	s_waitcnt vmcnt(2)
	ds_write_b128 v125, v[24:27] offset:32768
	s_waitcnt vmcnt(1)
	ds_write_b128 v126, v[28:31] offset:32768
	s_waitcnt vmcnt(0)
	ds_write_b128 v127, v[32:35] offset:32768
	s_waitcnt lgkmcnt(0)
	s_barrier
	ds_read_b128 v[0:3], v116
	ds_read_b128 v[4:7], v116 offset:2048
	ds_read_b128 v[8:11], v116 offset:4096
	ds_read_b128 v[12:15], v116 offset:6144
	ds_read_b128 v[16:19], v117 offset:32768
	ds_read_b128 v[20:23], v117 offset:34816
	ds_read_b128 v[24:27], v117 offset:36864
	ds_read_b128 v[28:31], v117 offset:38912
	s_waitcnt lgkmcnt(3)
	v_mfma_f32_16x16x32_bf16 v[32:35], v[16:19], v[0:3], 0
	s_waitcnt lgkmcnt(2)
	v_mfma_f32_16x16x32_bf16 v[36:39], v[20:23], v[0:3], 0
	s_waitcnt lgkmcnt(1)
	v_mfma_f32_16x16x32_bf16 v[40:43], v[24:27], v[0:3], 0
	s_waitcnt lgkmcnt(0)
	v_mfma_f32_16x16x32_bf16 v[0:3], v[28:31], v[0:3], 0
	v_mfma_f32_16x16x32_bf16 v[44:47], v[16:19], v[4:7], 0
	v_mfma_f32_16x16x32_bf16 v[48:51], v[20:23], v[4:7], 0
	v_mfma_f32_16x16x32_bf16 v[52:55], v[24:27], v[4:7], 0
	v_mfma_f32_16x16x32_bf16 v[4:7], v[28:31], v[4:7], 0
	v_mfma_f32_16x16x32_bf16 v[56:59], v[16:19], v[8:11], 0
	v_mfma_f32_16x16x32_bf16 v[60:63], v[20:23], v[8:11], 0
	v_mfma_f32_16x16x32_bf16 v[64:67], v[24:27], v[8:11], 0
	v_mfma_f32_16x16x32_bf16 v[8:11], v[28:31], v[8:11], 0
	v_mfma_f32_16x16x32_bf16 v[16:19], v[16:19], v[12:15], 0
	v_mfma_f32_16x16x32_bf16 v[20:23], v[20:23], v[12:15], 0
	v_mfma_f32_16x16x32_bf16 v[24:27], v[24:27], v[12:15], 0
	v_mfma_f32_16x16x32_bf16 v[12:15], v[28:31], v[12:15], 0
	ds_read_b128 v[28:31], v118
	ds_read_b128 v[68:71], v118 offset:2048
	ds_read_b128 v[154:157], v118 offset:4096
	ds_read_b128 v[158:161], v118 offset:6144
	ds_read_b128 v[162:165], v119 offset:32768
	ds_read_b128 v[166:169], v119 offset:34816
	ds_read_b128 v[170:173], v119 offset:36864
	ds_read_b128 v[178:181], v119 offset:38912
	s_waitcnt lgkmcnt(3)
	v_mfma_f32_16x16x32_bf16 v[32:35], v[162:165], v[28:31], v[32:35]
	s_waitcnt lgkmcnt(2)
	v_mfma_f32_16x16x32_bf16 v[36:39], v[166:169], v[28:31], v[36:39]
	s_waitcnt lgkmcnt(1)
	v_mfma_f32_16x16x32_bf16 v[40:43], v[170:173], v[28:31], v[40:43]
	s_waitcnt lgkmcnt(0)
	v_mfma_f32_16x16x32_bf16 v[0:3], v[178:181], v[28:31], v[0:3]
	v_mfma_f32_16x16x32_bf16 v[28:31], v[162:165], v[68:71], v[44:47]
	v_mfma_f32_16x16x32_bf16 v[44:47], v[166:169], v[68:71], v[48:51]
	v_mfma_f32_16x16x32_bf16 v[48:51], v[170:173], v[68:71], v[52:55]
	v_mfma_f32_16x16x32_bf16 v[52:55], v[162:165], v[154:157], v[56:59]
	v_mfma_f32_16x16x32_bf16 v[4:7], v[178:181], v[68:71], v[4:7]
	v_mfma_f32_16x16x32_bf16 v[56:59], v[166:169], v[154:157], v[60:63]
	v_mfma_f32_16x16x32_bf16 v[60:63], v[170:173], v[154:157], v[64:67]
	v_mfma_f32_16x16x32_bf16 v[8:11], v[178:181], v[154:157], v[8:11]
	v_mfma_f32_16x16x32_bf16 v[16:19], v[162:165], v[158:161], v[16:19]
	v_mfma_f32_16x16x32_bf16 v[20:23], v[166:169], v[158:161], v[20:23]
	v_mfma_f32_16x16x32_bf16 v[24:27], v[170:173], v[158:161], v[24:27]
	v_mfma_f32_16x16x32_bf16 v[12:15], v[178:181], v[158:161], v[12:15]
	ds_read_b128 v[64:67], v116 offset:16384
	ds_read_b128 v[68:71], v116 offset:18432
	ds_read_b128 v[154:157], v116 offset:20480
	ds_read_b128 v[158:161], v116 offset:22528
	ds_read_b128 v[162:165], v117 offset:49152
	ds_read_b128 v[166:169], v117 offset:51200
	ds_read_b128 v[170:173], v117 offset:53248
	ds_read_b128 v[178:181], v117 offset:55296
	s_waitcnt lgkmcnt(3)
	v_mfma_f32_16x16x32_bf16 v[52:55], v[162:165], v[154:157], v[52:55]
	v_mfma_f32_16x16x32_bf16 v[32:35], v[162:165], v[64:67], v[32:35]
	s_waitcnt lgkmcnt(2)
	v_mfma_f32_16x16x32_bf16 v[36:39], v[166:169], v[64:67], v[36:39]
	s_waitcnt lgkmcnt(1)
	v_mfma_f32_16x16x32_bf16 v[40:43], v[170:173], v[64:67], v[40:43]
	s_waitcnt lgkmcnt(0)
	v_mfma_f32_16x16x32_bf16 v[0:3], v[178:181], v[64:67], v[0:3]
	v_mfma_f32_16x16x32_bf16 v[182:185], v[162:165], v[68:71], v[28:31]
	v_mfma_f32_16x16x32_bf16 v[186:189], v[166:169], v[68:71], v[44:47]
	v_mfma_f32_16x16x32_bf16 v[48:51], v[170:173], v[68:71], v[48:51]
	v_mfma_f32_16x16x32_bf16 v[4:7], v[178:181], v[68:71], v[4:7]
	v_mfma_f32_16x16x32_bf16 v[68:71], v[166:169], v[154:157], v[56:59]
	v_mfma_f32_16x16x32_bf16 v[220:223], v[170:173], v[154:157], v[60:63]
	v_mfma_f32_16x16x32_bf16 v[154:157], v[178:181], v[154:157], v[8:11]
	v_mfma_f32_16x16x32_bf16 v[16:19], v[162:165], v[158:161], v[16:19]
	v_mfma_f32_16x16x32_bf16 v[162:165], v[166:169], v[158:161], v[20:23]
	v_mfma_f32_16x16x32_bf16 v[166:169], v[170:173], v[158:161], v[24:27]
	v_mfma_f32_16x16x32_bf16 v[158:161], v[178:181], v[158:161], v[12:15]
	ds_read_b128 v[8:11], v118 offset:16384
	ds_read_b128 v[20:23], v118 offset:18432
	ds_read_b128 v[170:173], v118 offset:20480
	ds_read_b128 v[178:181], v118 offset:22528
	ds_read_b128 v[224:227], v119 offset:49152
	ds_read_b128 v[228:231], v119 offset:51200
	ds_read_b128 v[232:235], v119 offset:53248
	ds_read_b128 v[236:239], v119 offset:55296
	s_waitcnt lgkmcnt(3)
	v_mfma_f32_16x16x32_bf16 v[56:59], v[224:227], v[170:173], v[52:55]
	s_nop 2
	v_or_b32_e32 v52, v100, v76
	v_ashrrev_i32_e32 v53, 31, v52
	s_waitcnt lgkmcnt(2)
	v_mfma_f32_16x16x32_bf16 v[44:47], v[228:231], v[8:11], v[36:39]
	v_mfma_f32_16x16x32_bf16 v[36:39], v[228:231], v[170:173], v[68:71]
	s_nop 2
	v_lshlrev_b64 v[68:69], 2, v[52:53]
	v_lshl_add_u64 v[52:53], s[18:19], 0, v[68:69]
	v_lshl_add_u64 v[68:69], s[20:21], 0, v[68:69]
	global_load_dwordx4 v[68:71], v[68:69], off
	v_mfma_f32_16x16x32_bf16 v[64:67], v[224:227], v[8:11], v[32:35]
	global_load_dwordx4 v[52:55], v[52:53], off
	s_waitcnt vmcnt(1)
	v_mul_f32_e32 v68, 0xbfb8aa3b, v68
	v_exp_f32_e32 v68, v68
	s_waitcnt lgkmcnt(1)
	v_mfma_f32_16x16x32_bf16 v[28:31], v[232:235], v[8:11], v[40:43]
	v_add_f32_e32 v68, 1.0, v68
	v_cmp_gt_f32_e32 vcc, s0, v68
	s_mov_b32 s0, 0x3f317217
	s_waitcnt lgkmcnt(0)
	v_mfma_f32_16x16x32_bf16 v[12:15], v[236:239], v[8:11], v[0:3]
	v_cndmask_b32_e64 v96, 0, 32, vcc
	v_ldexp_f32 v68, v68, v96
	v_log_f32_e32 v68, v68
	v_mfma_f32_16x16x32_bf16 v[8:11], v[236:239], v[20:23], v[4:7]
	v_mul_f32_e32 v96, 0x3f317217, v68
	v_fma_f32 v96, v68, s0, -v96
	v_fmac_f32_e32 v96, 0x3377d1cf, v68
	s_mov_b32 s0, 0x7f800000
	v_fmac_f32_e32 v96, 0x3f317217, v68
	v_cmp_lt_f32_e64 s[0:1], |v68|, s0
	v_mfma_f32_16x16x32_bf16 v[4:7], v[236:239], v[170:173], v[154:157]
	s_nop 0
	v_cndmask_b32_e64 v68, v68, v96, s[0:1]
	v_cndmask_b32_e32 v96, 0, v217, vcc
	v_add_u32_e32 v154, v109, v110
	v_sub_f32_e32 v68, v68, v96
	ds_read_b64 v[96:97], v154
	v_mfma_f32_16x16x32_bf16 v[60:63], v[224:227], v[20:23], v[182:185]
	v_mul_f32_e32 v153, 0xc1000000, v68
	v_lshlrev_b32_e32 v68, 16, v152
	v_mul_f32_e32 v68, v153, v68
	v_mfma_f32_16x16x32_bf16 v[40:43], v[228:231], v[20:23], v[186:189]
	v_add_f32_e32 v155, v68, v68
	s_mov_b32 s0, 0xbca3d70a
	v_cmp_nlt_f32_e32 vcc, s0, v155
	v_mfma_f32_16x16x32_bf16 v[24:27], v[232:235], v[20:23], v[48:51]
	v_mfma_f32_16x16x32_bf16 v[20:23], v[232:235], v[170:173], v[220:223]
	v_mfma_f32_16x16x32_bf16 v[48:51], v[224:227], v[178:181], v[16:19]
	v_mfma_f32_16x16x32_bf16 v[32:35], v[228:231], v[178:181], v[162:165]
	v_mfma_f32_16x16x32_bf16 v[16:19], v[232:235], v[178:181], v[166:169]
	v_mfma_f32_16x16x32_bf16 v[0:3], v[236:239], v[178:181], v[158:161]
	s_and_saveexec_b64 s[0:1], vcc
	s_xor_b64 s[0:1], exec, s[0:1]
	v_mul_f32_e32 v155, 0x3fb8aa3b, v155
	v_exp_f32_e32 v155, v155
	s_nop 0
	v_sub_f32_e32 v157, 1.0, v155
	s_andn2_saveexec_b64 s[0:1], s[0:1]
	s_mov_b32 s2, 0x3e2aaaab
	v_fma_f32 v156, v155, s2, 0.5
	v_fma_f32 v156, v155, v156, 1.0
	v_mul_f32_e64 v157, v156, -v155
	s_or_b64 exec, exec, s[0:1]
	v_mul_f32_e32 v69, 0xbfb8aa3b, v69
	v_exp_f32_e32 v69, v69
	s_mov_b32 s0, 0x800000
	v_add_f32_e32 v69, 1.0, v69
	v_cmp_gt_f32_e32 vcc, s0, v69
	s_mov_b32 s0, 0x3f317217
	s_nop 0
	v_cndmask_b32_e64 v155, 0, 32, vcc
	v_ldexp_f32 v69, v69, v155
	v_log_f32_e32 v69, v69
	v_cndmask_b32_e32 v155, 0, v217, vcc
	v_mul_f32_e32 v156, 0x3f317217, v69
	v_fma_f32 v156, v69, s0, -v156
	v_fmac_f32_e32 v156, 0x3377d1cf, v69
	s_mov_b32 s0, 0x7f800000
	v_fmac_f32_e32 v156, 0x3f317217, v69
	v_cmp_lt_f32_e64 vcc, |v69|, s0
	s_mov_b32 s0, 0xbca3d70a
	s_nop 0
	v_cndmask_b32_e32 v69, v69, v156, vcc
	v_sub_f32_e32 v69, v69, v155
	v_mul_f32_e32 v155, 0xc1000000, v69
	v_and_b32_e32 v69, 0xffff0000, v152
	v_mul_f32_e32 v69, v155, v69
	v_add_f32_e32 v152, v69, v69
	v_cmp_nlt_f32_e32 vcc, s0, v152
	s_and_saveexec_b64 s[0:1], vcc
	s_xor_b64 s[0:1], exec, s[0:1]
	v_mul_f32_e32 v152, 0x3fb8aa3b, v152
	v_exp_f32_e32 v152, v152
	s_nop 0
	v_sub_f32_e32 v158, 1.0, v152
	s_andn2_saveexec_b64 s[0:1], s[0:1]
	s_mov_b32 s2, 0x3e2aaaab
	v_fma_f32 v156, v152, s2, 0.5
	v_fma_f32 v156, v152, v156, 1.0
	v_mul_f32_e64 v158, v156, -v152
	s_or_b64 exec, exec, s[0:1]
	v_mul_f32_e32 v70, 0xbfb8aa3b, v70
	v_exp_f32_e32 v70, v70
	s_mov_b32 s0, 0x800000
	v_add_f32_e32 v70, 1.0, v70
	v_cmp_gt_f32_e32 vcc, s0, v70
	s_mov_b32 s0, 0x3f317217
	s_nop 0
	v_cndmask_b32_e64 v152, 0, 32, vcc
	v_ldexp_f32 v70, v70, v152
	v_log_f32_e32 v70, v70
	v_cndmask_b32_e32 v152, 0, v217, vcc
	v_mul_f32_e32 v156, 0x3f317217, v70
	v_fma_f32 v156, v70, s0, -v156
	v_fmac_f32_e32 v156, 0x3377d1cf, v70
	s_mov_b32 s0, 0x7f800000
	v_fmac_f32_e32 v156, 0x3f317217, v70
	v_cmp_lt_f32_e64 vcc, |v70|, s0
	s_mov_b32 s0, 0xbca3d70a
	s_nop 0
	v_cndmask_b32_e32 v70, v70, v156, vcc
	v_sub_f32_e32 v70, v70, v152
	v_mul_f32_e32 v152, 0xc1000000, v70
	v_lshlrev_b32_e32 v70, 16, v105
	v_mul_f32_e32 v70, v152, v70
	v_add_f32_e32 v156, v70, v70
	v_cmp_nlt_f32_e32 vcc, s0, v156
	s_and_saveexec_b64 s[0:1], vcc
	s_xor_b64 s[0:1], exec, s[0:1]
	v_mul_f32_e32 v156, 0x3fb8aa3b, v156
	v_exp_f32_e32 v156, v156
	s_nop 0
	v_sub_f32_e32 v159, 1.0, v156
	s_andn2_saveexec_b64 s[0:1], s[0:1]
	s_mov_b32 s2, 0x3e2aaaab
	v_fma_f32 v159, v156, s2, 0.5
	v_fma_f32 v159, v156, v159, 1.0
	v_mul_f32_e64 v159, v159, -v156
	s_or_b64 exec, exec, s[0:1]
	v_mul_f32_e32 v71, 0xbfb8aa3b, v71
	v_exp_f32_e32 v71, v71
	s_mov_b32 s0, 0x800000
	v_add_f32_e32 v71, 1.0, v71
	v_cmp_gt_f32_e32 vcc, s0, v71
	s_mov_b32 s0, 0x3f317217
	s_nop 0
	v_cndmask_b32_e64 v156, 0, 32, vcc
	v_ldexp_f32 v71, v71, v156
	v_log_f32_e32 v71, v71
	v_cndmask_b32_e32 v156, 0, v217, vcc
	v_mul_f32_e32 v160, 0x3f317217, v71
	v_fma_f32 v160, v71, s0, -v160
	v_fmac_f32_e32 v160, 0x3377d1cf, v71
	s_mov_b32 s0, 0x7f800000
	v_fmac_f32_e32 v160, 0x3f317217, v71
	v_cmp_lt_f32_e64 vcc, |v71|, s0
	s_mov_b32 s0, 0xbca3d70a
	s_nop 0
	v_cndmask_b32_e32 v71, v71, v160, vcc
	v_sub_f32_e32 v71, v71, v156
	v_mul_f32_e32 v156, 0xc1000000, v71
	v_and_b32_e32 v71, 0xffff0000, v105
	v_mul_f32_e32 v71, v156, v71
	v_add_f32_e32 v160, v71, v71
	v_cmp_nlt_f32_e32 vcc, s0, v160
	s_and_saveexec_b64 s[0:1], vcc
	s_xor_b64 s[0:1], exec, s[0:1]
	v_mul_f32_e32 v105, 0x3fb8aa3b, v160
	v_exp_f32_e32 v105, v105
	s_nop 0
	v_sub_f32_e32 v105, 1.0, v105
	s_andn2_saveexec_b64 s[0:1], s[0:1]
	s_mov_b32 s2, 0x3e2aaaab
	v_fma_f32 v105, v160, s2, 0.5
	v_fma_f32 v105, v160, v105, 1.0
	v_mul_f32_e64 v105, v105, -v160
	s_or_b64 exec, exec, s[0:1]
	s_waitcnt vmcnt(0)
	v_add_f32_e32 v66, v66, v54
	v_mul_f32_e32 v66, 0xbfb8aa3b, v66
	v_add_f32_e32 v65, v65, v53
	v_exp_f32_e32 v66, v66
	v_mul_f32_e32 v65, 0xbfb8aa3b, v65
	v_exp_f32_e32 v65, v65
	v_max_f32_e32 v159, v159, v159
	v_max_f32_e32 v159, 0, v159
	v_add_f32_e32 v66, 1.0, v66
	v_add_f32_e32 v67, v67, v55
	v_max_f32_e32 v158, v158, v158
	v_sqrt_f32_e32 v159, v159
	v_rcp_f32_e32 v66, v66
	v_mul_f32_e32 v67, 0xbfb8aa3b, v67
	v_add_f32_e32 v65, 1.0, v65
	v_max_f32_e32 v158, 0, v158
	v_exp_f32_e32 v67, v67
	v_rcp_f32_e32 v65, v65
	v_sqrt_f32_e32 v158, v158
	v_add_f32_e32 v64, v64, v52
	v_mul_f32_e32 v64, 0xbfb8aa3b, v64
	v_exp_f32_e32 v64, v64
	s_waitcnt lgkmcnt(0)
	v_lshlrev_b32_e32 v160, 16, v97
	v_mul_f32_e32 v66, v66, v159
	v_mul_f32_e32 v159, v66, v160
	v_add_f32_e32 v66, 1.0, v67
	v_and_b32_e32 v67, 0xffff0000, v96
	v_mul_f32_e32 v65, v65, v158
	v_mul_f32_e32 v65, v65, v67
	v_lshlrev_b32_e32 v67, 16, v96
	v_max_f32_e32 v96, v157, v157
	v_add_f32_e32 v64, 1.0, v64
	v_max_f32_e32 v96, 0, v96
	v_max_f32_e32 v105, v105, v105
	v_rcp_f32_e32 v64, v64
	v_sqrt_f32_e32 v96, v96
	v_max_f32_e32 v105, 0, v105
	v_rcp_f32_e32 v66, v66
	v_sqrt_f32_e32 v105, v105
	v_mul_f32_e32 v64, v64, v96
	v_mul_f32_e32 v64, v64, v67
	v_and_b32_e32 v67, 0xffff0000, v97
	v_mul_f32_e32 v66, v66, v105
	v_mul_f32_e32 v96, v66, v67
	s_nop 1
	v_cvt_pk_bf16_f32 v66, v68, v69
	v_add_u32_e32 v68, v109, v112
	ds_read_b64 v[68:69], v68
	s_nop 1
	v_cvt_pk_bf16_f32 v67, v70, v71
	v_lshlrev_b32_e32 v70, 16, v104
	v_mul_f32_e32 v70, v153, v70
	s_nop 1
	v_cvt_pk_bf16_f32 v64, v64, v65
	s_nop 1
	v_cvt_pk_bf16_f32 v65, v159, v96
	v_add_f32_e32 v96, v70, v70
	s_mov_b32 s0, 0xbca3d70a
	v_cmp_nlt_f32_e32 vcc, s0, v96
	s_and_saveexec_b64 s[0:1], vcc
	s_xor_b64 s[0:1], exec, s[0:1]
	v_mul_f32_e32 v71, 0x3fb8aa3b, v96
	v_exp_f32_e32 v71, v71
	s_nop 0
	v_sub_f32_e32 v71, 1.0, v71
	s_andn2_saveexec_b64 s[0:1], s[0:1]
	s_mov_b32 s2, 0x3e2aaaab
	v_fma_f32 v71, v96, s2, 0.5
	v_fma_f32 v71, v96, v71, 1.0
	v_mul_f32_e64 v71, v71, -v96
	s_or_b64 exec, exec, s[0:1]
	v_and_b32_e32 v96, 0xffff0000, v104
	v_mul_f32_e32 v96, v155, v96
	v_add_f32_e32 v97, v96, v96
	s_mov_b32 s0, 0xbca3d70a
	v_cmp_nlt_f32_e32 vcc, s0, v97
	s_and_saveexec_b64 s[0:1], vcc
	s_xor_b64 s[0:1], exec, s[0:1]
	v_mul_f32_e32 v97, 0x3fb8aa3b, v97
	v_exp_f32_e32 v97, v97
	s_nop 0
	v_sub_f32_e32 v104, 1.0, v97
	s_andn2_saveexec_b64 s[0:1], s[0:1]
	s_mov_b32 s2, 0x3e2aaaab
	v_fma_f32 v104, v97, s2, 0.5
	v_fma_f32 v104, v97, v104, 1.0
	v_mul_f32_e64 v104, v104, -v97
	s_or_b64 exec, exec, s[0:1]
	v_lshlrev_b32_e32 v97, 16, v103
	v_mul_f32_e32 v105, v152, v97
	v_add_f32_e32 v97, v105, v105
	s_mov_b32 s0, 0xbca3d70a
	v_cmp_nlt_f32_e32 vcc, s0, v97
	s_and_saveexec_b64 s[0:1], vcc
	s_xor_b64 s[0:1], exec, s[0:1]
	v_mul_f32_e32 v97, 0x3fb8aa3b, v97
	v_exp_f32_e32 v97, v97
	s_nop 0
	v_sub_f32_e32 v157, 1.0, v97
	s_andn2_saveexec_b64 s[0:1], s[0:1]
	s_mov_b32 s2, 0x3e2aaaab
	v_fma_f32 v157, v97, s2, 0.5
	v_fma_f32 v157, v97, v157, 1.0
	v_mul_f32_e64 v157, v157, -v97
	s_or_b64 exec, exec, s[0:1]
	v_and_b32_e32 v97, 0xffff0000, v103
	v_mul_f32_e32 v97, v156, v97
	v_add_f32_e32 v158, v97, v97
	s_mov_b32 s0, 0xbca3d70a
	v_cmp_nlt_f32_e32 vcc, s0, v158
	s_and_saveexec_b64 s[0:1], vcc
	s_xor_b64 s[0:1], exec, s[0:1]
	v_mul_f32_e32 v103, 0x3fb8aa3b, v158
	v_exp_f32_e32 v103, v103
	s_nop 0
	v_sub_f32_e32 v103, 1.0, v103
	s_andn2_saveexec_b64 s[0:1], s[0:1]
	s_mov_b32 s2, 0x3e2aaaab
	v_fma_f32 v103, v158, s2, 0.5
	v_fma_f32 v103, v158, v103, 1.0
	v_mul_f32_e64 v103, v103, -v158
	s_or_b64 exec, exec, s[0:1]
	v_add_f32_e32 v62, v62, v54
	v_add_f32_e32 v60, v60, v52
	v_mul_f32_e32 v62, 0xbfb8aa3b, v62
	v_mul_f32_e32 v60, 0xbfb8aa3b, v60
	v_exp_f32_e32 v62, v62
	v_exp_f32_e32 v60, v60
	v_max_f32_e32 v157, v157, v157
	v_max_f32_e32 v71, v71, v71
	v_add_f32_e32 v62, 1.0, v62
	v_max_f32_e32 v157, 0, v157
	v_add_f32_e32 v61, v61, v53
	v_add_f32_e32 v60, 1.0, v60
	v_max_f32_e32 v71, 0, v71
	v_rcp_f32_e32 v62, v62
	v_sqrt_f32_e32 v157, v157
	v_add_f32_e32 v63, v63, v55
	v_mul_f32_e32 v61, 0xbfb8aa3b, v61
	v_rcp_f32_e32 v60, v60
	v_sqrt_f32_e32 v71, v71
	v_mul_f32_e32 v63, 0xbfb8aa3b, v63
	v_exp_f32_e32 v61, v61
	v_exp_f32_e32 v63, v63
	v_add_u32_e32 v158, s31, v111
	s_movk_i32 s0, 0x2010
	v_cmp_eq_u32_e32 vcc, s0, v158
	v_mul_f32_e32 v62, v62, v157
	s_waitcnt lgkmcnt(0)
	v_and_b32_e32 v157, 0xffff0000, v68
	v_max_f32_e32 v104, v104, v104
	v_lshlrev_b32_e32 v68, 16, v68
	v_mul_f32_e32 v60, v60, v71
	v_add_f32_e32 v61, 1.0, v61
	v_max_f32_e32 v104, 0, v104
	v_mul_f32_e32 v60, v60, v68
	v_cndmask_b32_e32 v68, v70, v218, vcc
	v_max_f32_e32 v70, v103, v103
	v_add_f32_e32 v63, 1.0, v63
	v_rcp_f32_e32 v61, v61
	v_sqrt_f32_e32 v104, v104
	v_max_f32_e32 v70, 0, v70
	v_rcp_f32_e32 v63, v63
	v_sqrt_f32_e32 v70, v70
	v_mul_f32_e32 v61, v61, v104
	v_lshlrev_b32_e32 v158, 16, v69
	v_mul_f32_e32 v61, v61, v157
	v_cndmask_b32_e32 v96, v96, v218, vcc
	v_and_b32_e32 v69, 0xffff0000, v69
	v_mul_f32_e32 v63, v63, v70
	v_mul_f32_e32 v62, v62, v158
	v_mul_f32_e32 v63, v63, v69
	v_cndmask_b32_e32 v69, v97, v218, vcc
	s_nop 1
	v_cvt_pk_bf16_f32 v96, v68, v96
	s_nop 1
	v_cvt_pk_bf16_f32 v68, v60, v61
	ds_read_b64 v[60:61], v154 offset:4096
	v_cndmask_b32_e32 v105, v105, v218, vcc
	s_nop 1
	v_cvt_pk_bf16_f32 v97, v105, v69
	s_nop 1
	v_cvt_pk_bf16_f32 v69, v62, v63
	v_lshlrev_b32_e32 v62, 16, v99
	v_mul_f32_e32 v62, v153, v62
	v_add_f32_e32 v70, v62, v62
	s_mov_b32 s0, 0xbca3d70a
	v_cmp_nlt_f32_e64 s[0:1], s0, v70
	s_and_saveexec_b64 s[2:3], s[0:1]
	s_xor_b64 s[0:1], exec, s[2:3]
	v_mul_f32_e32 v63, 0x3fb8aa3b, v70
	v_exp_f32_e32 v63, v63
	s_nop 0
	v_sub_f32_e32 v63, 1.0, v63
	s_andn2_saveexec_b64 s[0:1], s[0:1]
	s_mov_b32 s2, 0x3e2aaaab
	v_fma_f32 v63, v70, s2, 0.5
	v_fma_f32 v63, v70, v63, 1.0
	v_mul_f32_e64 v63, v63, -v70
	s_or_b64 exec, exec, s[0:1]
	v_and_b32_e32 v70, 0xffff0000, v99
	v_mul_f32_e32 v70, v155, v70
	v_add_f32_e32 v71, v70, v70
	s_mov_b32 s0, 0xbca3d70a
	v_cmp_nlt_f32_e64 s[0:1], s0, v71
	s_and_saveexec_b64 s[2:3], s[0:1]
	s_xor_b64 s[0:1], exec, s[2:3]
	v_mul_f32_e32 v71, 0x3fb8aa3b, v71
	v_exp_f32_e32 v71, v71
	s_nop 0
	v_sub_f32_e32 v99, 1.0, v71
	s_andn2_saveexec_b64 s[0:1], s[0:1]
	s_mov_b32 s2, 0x3e2aaaab
	v_fma_f32 v99, v71, s2, 0.5
	v_fma_f32 v99, v71, v99, 1.0
	v_mul_f32_e64 v99, v99, -v71
	s_or_b64 exec, exec, s[0:1]
	v_lshlrev_b32_e32 v71, 16, v98
	v_mul_f32_e32 v71, v152, v71
	v_add_f32_e32 v103, v71, v71
	s_mov_b32 s0, 0xbca3d70a
	v_cmp_nlt_f32_e64 s[0:1], s0, v103
	s_and_saveexec_b64 s[2:3], s[0:1]
	s_xor_b64 s[0:1], exec, s[2:3]
	v_mul_f32_e32 v103, 0x3fb8aa3b, v103
	v_exp_f32_e32 v103, v103
	s_nop 0
	v_sub_f32_e32 v104, 1.0, v103
	s_andn2_saveexec_b64 s[0:1], s[0:1]
	s_mov_b32 s2, 0x3e2aaaab
	v_fma_f32 v104, v103, s2, 0.5
	v_fma_f32 v104, v103, v104, 1.0
	v_mul_f32_e64 v104, v104, -v103
	s_or_b64 exec, exec, s[0:1]
	v_and_b32_e32 v98, 0xffff0000, v98
	v_mul_f32_e32 v103, v156, v98
	v_add_f32_e32 v105, v103, v103
	s_mov_b32 s0, 0xbca3d70a
	v_cmp_nlt_f32_e64 s[0:1], s0, v105
	s_and_saveexec_b64 s[2:3], s[0:1]
	s_xor_b64 s[0:1], exec, s[2:3]
	v_mul_f32_e32 v98, 0x3fb8aa3b, v105
	v_exp_f32_e32 v98, v98
	s_nop 0
	v_sub_f32_e32 v98, 1.0, v98
	s_andn2_saveexec_b64 s[0:1], s[0:1]
	s_mov_b32 s2, 0x3e2aaaab
	v_fma_f32 v98, v105, s2, 0.5
	v_fma_f32 v98, v105, v98, 1.0
	v_mul_f32_e64 v98, v98, -v105
	s_or_b64 exec, exec, s[0:1]
	v_add_f32_e32 v58, v58, v54
	v_add_f32_e32 v57, v57, v53
	v_add_f32_e32 v56, v56, v52
	v_mul_f32_e32 v58, 0xbfb8aa3b, v58
	v_mul_f32_e32 v57, 0xbfb8aa3b, v57
	v_mul_f32_e32 v56, 0xbfb8aa3b, v56
	v_exp_f32_e32 v58, v58
	v_add_f32_e32 v59, v59, v55
	v_exp_f32_e32 v57, v57
	v_exp_f32_e32 v56, v56
	v_mul_f32_e32 v59, 0xbfb8aa3b, v59
	v_exp_f32_e32 v59, v59
	v_max_f32_e32 v104, v104, v104
	v_max_f32_e32 v99, v99, v99
	v_max_f32_e32 v63, v63, v63
	v_max_f32_e32 v104, 0, v104
	v_add_f32_e32 v58, 1.0, v58
	v_add_f32_e32 v57, 1.0, v57
	v_max_f32_e32 v99, 0, v99
	v_add_f32_e32 v56, 1.0, v56
	v_max_f32_e32 v63, 0, v63
	v_sqrt_f32_e32 v104, v104
	v_rcp_f32_e32 v58, v58
	v_rcp_f32_e32 v57, v57
	v_sqrt_f32_e32 v99, v99
	v_rcp_f32_e32 v56, v56
	v_sqrt_f32_e32 v63, v63
	v_max_f32_e32 v98, v98, v98
	v_add_f32_e32 v59, 1.0, v59
	v_max_f32_e32 v98, 0, v98
	v_rcp_f32_e32 v59, v59
	v_sqrt_f32_e32 v98, v98
	s_waitcnt lgkmcnt(0)
	v_lshlrev_b32_e32 v105, 16, v61
	v_mul_f32_e32 v58, v58, v104
	v_and_b32_e32 v104, 0xffff0000, v60
	v_mul_f32_e32 v57, v57, v99
	v_lshlrev_b32_e32 v60, 16, v60
	v_mul_f32_e32 v56, v56, v63
	v_mul_f32_e32 v58, v58, v105
	v_mul_f32_e32 v57, v57, v104
	v_mul_f32_e32 v56, v56, v60
	ds_read_b64 v[104:105], v154 offset:6144
	v_mul_f32_e32 v59, v59, v98
	s_nop 1
	v_cvt_pk_bf16_f32 v98, v62, v70
	s_nop 1
	v_cvt_pk_bf16_f32 v70, v56, v57
	v_lshlrev_b32_e32 v56, 16, v102
	v_mul_f32_e32 v153, v153, v56
	v_add_f32_e32 v56, v153, v153
	s_mov_b32 s0, 0xbca3d70a
	v_and_b32_e32 v60, 0xffff0000, v61
	v_cmp_nlt_f32_e64 s[0:1], s0, v56
	v_mul_f32_e32 v59, v59, v60
	s_nop 1
	v_cvt_pk_bf16_f32 v99, v71, v103
	s_nop 1
	v_cvt_pk_bf16_f32 v71, v58, v59
	s_and_saveexec_b64 s[2:3], s[0:1]
	s_xor_b64 s[0:1], exec, s[2:3]
	v_mul_f32_e32 v56, 0x3fb8aa3b, v56
	v_exp_f32_e32 v56, v56
	s_nop 0
	v_sub_f32_e32 v154, 1.0, v56
	s_andn2_saveexec_b64 s[0:1], s[0:1]
	s_mov_b32 s2, 0x3e2aaaab
	v_fma_f32 v57, v56, s2, 0.5
	v_fma_f32 v57, v56, v57, 1.0
	v_mul_f32_e64 v154, v57, -v56
	s_or_b64 exec, exec, s[0:1]
	v_and_b32_e32 v56, 0xffff0000, v102
	v_mul_f32_e32 v155, v155, v56
	v_add_f32_e32 v56, v155, v155
	s_mov_b32 s0, 0xbca3d70a
	v_cmp_nlt_f32_e64 s[0:1], s0, v56
	s_and_saveexec_b64 s[2:3], s[0:1]
	s_xor_b64 s[0:1], exec, s[2:3]
	v_mul_f32_e32 v56, 0x3fb8aa3b, v56
	v_exp_f32_e32 v56, v56
	s_nop 0
	v_sub_f32_e32 v157, 1.0, v56
	s_andn2_saveexec_b64 s[0:1], s[0:1]
	s_mov_b32 s2, 0x3e2aaaab
	v_fma_f32 v57, v56, s2, 0.5
	v_fma_f32 v57, v56, v57, 1.0
	v_mul_f32_e64 v157, v57, -v56
	s_or_b64 exec, exec, s[0:1]
	v_lshlrev_b32_e32 v56, 16, v101
	v_mul_f32_e32 v152, v152, v56
	v_add_f32_e32 v56, v152, v152
	s_mov_b32 s0, 0xbca3d70a
	v_cmp_nlt_f32_e64 s[0:1], s0, v56
	s_and_saveexec_b64 s[2:3], s[0:1]
	s_xor_b64 s[0:1], exec, s[2:3]
	v_mul_f32_e32 v56, 0x3fb8aa3b, v56
	v_exp_f32_e32 v56, v56
	s_nop 0
	v_sub_f32_e32 v158, 1.0, v56
	s_andn2_saveexec_b64 s[0:1], s[0:1]
	s_mov_b32 s2, 0x3e2aaaab
	v_fma_f32 v57, v56, s2, 0.5
	v_fma_f32 v57, v56, v57, 1.0
	v_mul_f32_e64 v158, v57, -v56
	s_or_b64 exec, exec, s[0:1]
	v_and_b32_e32 v56, 0xffff0000, v101
	v_mul_f32_e32 v156, v156, v56
	v_add_f32_e32 v56, v156, v156
	s_mov_b32 s0, 0xbca3d70a
	v_cmp_nlt_f32_e64 s[0:1], s0, v56
	s_and_saveexec_b64 s[2:3], s[0:1]
	s_xor_b64 s[0:1], exec, s[2:3]
	v_mul_f32_e32 v56, 0x3fb8aa3b, v56
	v_exp_f32_e32 v56, v56
	s_nop 0
	v_sub_f32_e32 v159, 1.0, v56
	s_andn2_saveexec_b64 s[0:1], s[0:1]
	s_mov_b32 s2, 0x3e2aaaab
	v_fma_f32 v57, v56, s2, 0.5
	v_fma_f32 v57, v56, v57, 1.0
	v_mul_f32_e64 v159, v57, -v56
	s_or_b64 exec, exec, s[0:1]
	v_ashrrev_i32_e32 v101, 31, v100
	v_lshl_add_u64 v[56:57], v[100:101], 0, v[76:77]
	v_lshlrev_b64 v[56:57], 2, v[56:57]
	v_lshl_add_u64 v[100:101], s[20:21], 0, v[56:57]
	global_load_dwordx4 v[60:63], v[100:101], off offset:64
	v_lshl_add_u64 v[102:103], s[18:19], 0, v[56:57]
	global_load_dwordx4 v[56:59], v[102:103], off offset:64
	v_add_f32_e32 v55, v51, v55
	v_mul_f32_e32 v55, 0xbfb8aa3b, v55
	v_exp_f32_e32 v55, v55
	v_add_f32_e32 v54, v50, v54
	v_add_f32_e32 v49, v49, v53
	v_add_f32_e32 v48, v48, v52
	v_max_f32_e32 v52, v154, v154
	v_max_f32_e32 v154, v159, v159
	v_mul_f32_e32 v54, 0xbfb8aa3b, v54
	v_mul_f32_e32 v49, 0xbfb8aa3b, v49
	v_mul_f32_e32 v48, 0xbfb8aa3b, v48
	v_max_f32_e32 v154, 0, v154
	v_add_f32_e32 v55, 1.0, v55
	v_exp_f32_e32 v54, v54
	v_exp_f32_e32 v49, v49
	v_exp_f32_e32 v48, v48
	v_sqrt_f32_e32 v154, v154
	v_rcp_f32_e32 v55, v55
	v_max_f32_e32 v158, v158, v158
	v_max_f32_e32 v53, v157, v157
	s_mov_b32 s0, 0x800000
	s_waitcnt lgkmcnt(0)
	v_lshlrev_b32_e32 v160, 16, v105
	v_and_b32_e32 v105, 0xffff0000, v105
	s_nop 1
	v_cvt_pk_bf16_f32 v50, v153, v155
	s_nop 1
	v_cvt_pk_bf16_f32 v51, v152, v156
	v_max_f32_e32 v152, 0, v158
	v_max_f32_e32 v153, 0, v53
	v_max_f32_e32 v155, 0, v52
	v_add_f32_e32 v54, 1.0, v54
	v_add_f32_e32 v49, 1.0, v49
	v_add_f32_e32 v48, 1.0, v48
	v_mul_f32_e32 v55, v55, v154
	v_sqrt_f32_e32 v152, v152
	v_sqrt_f32_e32 v153, v153
	v_sqrt_f32_e32 v155, v155
	v_rcp_f32_e32 v54, v54
	v_rcp_f32_e32 v49, v49
	v_rcp_f32_e32 v48, v48
	v_mul_f32_e32 v55, v55, v105
	v_and_b32_e32 v161, 0xffff0000, v104
	v_lshlrev_b32_e32 v157, 16, v104
	v_mul_f32_e32 v54, v54, v152
	v_mul_f32_e32 v49, v49, v153
	v_mul_f32_e32 v48, v48, v155
	v_mul_f32_e32 v54, v54, v160
	v_mul_f32_e32 v49, v49, v161
	v_mul_f32_e32 v48, v48, v157
	s_nop 1
	v_cvt_pk_bf16_f32 v48, v48, v49
	s_nop 1
	v_cvt_pk_bf16_f32 v49, v54, v55
	v_add_u32_e32 v104, v113, v110
	ds_read_b64 v[52:53], v104
	s_waitcnt vmcnt(1)
	v_mul_f32_e32 v60, 0xbfb8aa3b, v60
	v_exp_f32_e32 v60, v60
	s_nop 0
	v_add_f32_e32 v60, 1.0, v60
	v_cmp_gt_f32_e64 s[0:1], s0, v60
	s_nop 1
	v_cndmask_b32_e64 v105, 0, 32, s[0:1]
	v_ldexp_f32 v60, v60, v105
	v_log_f32_e32 v60, v60
	v_cndmask_b32_e64 v54, 0, v217, s[0:1]
	s_mov_b32 s0, 0x3f317217
	v_mul_f32_e32 v55, 0x3f317217, v60
	v_fma_f32 v55, v60, s0, -v55
	v_fmac_f32_e32 v55, 0x3377d1cf, v60
	s_mov_b32 s0, 0x7f800000
	v_fmac_f32_e32 v55, 0x3f317217, v60
	v_cmp_lt_f32_e64 s[0:1], |v60|, s0
	s_nop 1
	v_cndmask_b32_e64 v55, v60, v55, s[0:1]
	v_sub_f32_e32 v54, v55, v54
	v_mul_f32_e32 v152, 0xc1000000, v54
	v_lshlrev_b32_e32 v54, 16, v151
	v_mul_f32_e32 v54, v152, v54
	v_add_f32_e32 v60, v54, v54
	s_mov_b32 s0, 0xbca3d70a
	v_cmp_nlt_f32_e64 s[0:1], s0, v60
	s_and_saveexec_b64 s[2:3], s[0:1]
	s_xor_b64 s[0:1], exec, s[2:3]
	v_mul_f32_e32 v55, 0x3fb8aa3b, v60
	v_exp_f32_e32 v55, v55
	s_nop 0
	v_sub_f32_e32 v55, 1.0, v55
	s_andn2_saveexec_b64 s[0:1], s[0:1]
	s_mov_b32 s2, 0x3e2aaaab
	v_fma_f32 v55, v60, s2, 0.5
	v_fma_f32 v55, v60, v55, 1.0
	v_mul_f32_e64 v55, v55, -v60
	s_or_b64 exec, exec, s[0:1]
	v_mul_f32_e32 v60, 0xbfb8aa3b, v61
	v_exp_f32_e32 v60, v60
	s_mov_b32 s0, 0x800000
	v_add_f32_e32 v60, 1.0, v60
	v_cmp_gt_f32_e64 s[0:1], s0, v60
	s_nop 1
	v_cndmask_b32_e64 v61, 0, 32, s[0:1]
	v_ldexp_f32 v60, v60, v61
	v_log_f32_e32 v60, v60
	v_cndmask_b32_e64 v61, 0, v217, s[0:1]
	s_mov_b32 s0, 0x3f317217
	v_mul_f32_e32 v105, 0x3f317217, v60
	v_fma_f32 v105, v60, s0, -v105
	v_fmac_f32_e32 v105, 0x3377d1cf, v60
	s_mov_b32 s0, 0x7f800000
	v_fmac_f32_e32 v105, 0x3f317217, v60
	v_cmp_lt_f32_e64 s[0:1], |v60|, s0
	s_nop 1
	v_cndmask_b32_e64 v60, v60, v105, s[0:1]
	v_sub_f32_e32 v60, v60, v61
	v_mul_f32_e32 v153, 0xc1000000, v60
	v_and_b32_e32 v60, 0xffff0000, v151
	v_mul_f32_e32 v60, v153, v60
	v_add_f32_e32 v105, v60, v60
	s_mov_b32 s0, 0xbca3d70a
	v_cmp_nlt_f32_e64 s[0:1], s0, v105
	s_and_saveexec_b64 s[2:3], s[0:1]
	s_xor_b64 s[0:1], exec, s[2:3]
	v_mul_f32_e32 v61, 0x3fb8aa3b, v105
	v_exp_f32_e32 v61, v61
	s_nop 0
	v_sub_f32_e32 v61, 1.0, v61
	s_andn2_saveexec_b64 s[0:1], s[0:1]
	s_mov_b32 s2, 0x3e2aaaab
	v_fma_f32 v61, v105, s2, 0.5
	v_fma_f32 v61, v105, v61, 1.0
	v_mul_f32_e64 v61, v61, -v105
	s_or_b64 exec, exec, s[0:1]
	v_mul_f32_e32 v62, 0xbfb8aa3b, v62
	v_exp_f32_e32 v62, v62
	s_mov_b32 s0, 0x800000
	v_add_f32_e32 v62, 1.0, v62
	v_cmp_gt_f32_e64 s[0:1], s0, v62
	s_nop 1
	v_cndmask_b32_e64 v105, 0, 32, s[0:1]
	v_ldexp_f32 v62, v62, v105
	v_log_f32_e32 v62, v62
	v_cndmask_b32_e64 v105, 0, v217, s[0:1]
	s_mov_b32 s0, 0x3f317217
	v_mul_f32_e32 v151, 0x3f317217, v62
	v_fma_f32 v151, v62, s0, -v151
	v_fmac_f32_e32 v151, 0x3377d1cf, v62
	s_mov_b32 s0, 0x7f800000
	v_fmac_f32_e32 v151, 0x3f317217, v62
	v_cmp_lt_f32_e64 s[0:1], |v62|, s0
	s_nop 1
	v_cndmask_b32_e64 v62, v62, v151, s[0:1]
	v_sub_f32_e32 v62, v62, v105
	v_mul_f32_e32 v151, 0xc1000000, v62
	v_lshlrev_b32_e32 v62, 16, v150
	v_mul_f32_e32 v62, v151, v62
	v_add_f32_e32 v154, v62, v62
	s_mov_b32 s0, 0xbca3d70a
	v_cmp_nlt_f32_e64 s[0:1], s0, v154
	s_and_saveexec_b64 s[2:3], s[0:1]
	s_xor_b64 s[0:1], exec, s[2:3]
	v_mul_f32_e32 v105, 0x3fb8aa3b, v154
	v_exp_f32_e32 v105, v105
	s_nop 0
	v_sub_f32_e32 v105, 1.0, v105
	s_andn2_saveexec_b64 s[0:1], s[0:1]
	s_mov_b32 s2, 0x3e2aaaab
	v_fma_f32 v105, v154, s2, 0.5
	v_fma_f32 v105, v154, v105, 1.0
	v_mul_f32_e64 v105, v105, -v154
	s_or_b64 exec, exec, s[0:1]
	v_mul_f32_e32 v63, 0xbfb8aa3b, v63
	v_exp_f32_e32 v63, v63
	s_mov_b32 s0, 0x800000
	v_add_f32_e32 v63, 1.0, v63
	v_cmp_gt_f32_e64 s[0:1], s0, v63
	s_nop 1
	v_cndmask_b32_e64 v154, 0, 32, s[0:1]
	v_ldexp_f32 v63, v63, v154
	v_log_f32_e32 v63, v63
	v_cndmask_b32_e64 v154, 0, v217, s[0:1]
	s_mov_b32 s0, 0x3f317217
	v_mul_f32_e32 v155, 0x3f317217, v63
	v_fma_f32 v155, v63, s0, -v155
	v_fmac_f32_e32 v155, 0x3377d1cf, v63
	s_mov_b32 s0, 0x7f800000
	v_fmac_f32_e32 v155, 0x3f317217, v63
	v_cmp_lt_f32_e64 s[0:1], |v63|, s0
	s_nop 1
	v_cndmask_b32_e64 v63, v63, v155, s[0:1]
	v_sub_f32_e32 v63, v63, v154
	v_mul_f32_e32 v154, 0xc1000000, v63
	v_and_b32_e32 v63, 0xffff0000, v150
	v_mul_f32_e32 v63, v154, v63
	v_add_f32_e32 v155, v63, v63
	s_mov_b32 s0, 0xbca3d70a
	v_cmp_nlt_f32_e64 s[0:1], s0, v155
	s_and_saveexec_b64 s[2:3], s[0:1]
	s_xor_b64 s[0:1], exec, s[2:3]
	v_mul_f32_e32 v150, 0x3fb8aa3b, v155
	v_exp_f32_e32 v150, v150
	s_nop 0
	v_sub_f32_e32 v150, 1.0, v150
	s_andn2_saveexec_b64 s[0:1], s[0:1]
	s_mov_b32 s2, 0x3e2aaaab
	v_fma_f32 v150, v155, s2, 0.5
	v_fma_f32 v150, v155, v150, 1.0
	v_mul_f32_e64 v150, v150, -v155
	s_or_b64 exec, exec, s[0:1]
	s_waitcnt vmcnt(0)
	v_add_f32_e32 v45, v45, v57
	v_mul_f32_e32 v45, 0xbfb8aa3b, v45
	v_exp_f32_e32 v45, v45
	v_add_f32_e32 v46, v46, v58
	v_max_f32_e32 v61, v61, v61
	v_add_f32_e32 v44, v44, v56
	v_mul_f32_e32 v46, 0xbfb8aa3b, v46
	v_add_f32_e32 v47, v47, v59
	v_add_f32_e32 v45, 1.0, v45
	v_max_f32_e32 v61, 0, v61
	v_mul_f32_e32 v44, 0xbfb8aa3b, v44
	v_exp_f32_e32 v46, v46
	v_mul_f32_e32 v47, 0xbfb8aa3b, v47
	v_rcp_f32_e32 v45, v45
	v_sqrt_f32_e32 v61, v61
	v_exp_f32_e32 v44, v44
	v_exp_f32_e32 v47, v47
	v_max_f32_e32 v105, v105, v105
	v_max_f32_e32 v55, v55, v55
	v_max_f32_e32 v105, 0, v105
	v_add_f32_e32 v46, 1.0, v46
	v_mul_f32_e32 v45, v45, v61
	v_add_f32_e32 v44, 1.0, v44
	v_max_f32_e32 v55, 0, v55
	v_max_f32_e32 v61, v150, v150
	v_sqrt_f32_e32 v105, v105
	v_rcp_f32_e32 v46, v46
	v_add_f32_e32 v47, 1.0, v47
	v_rcp_f32_e32 v44, v44
	v_sqrt_f32_e32 v55, v55
	v_max_f32_e32 v61, 0, v61
	v_rcp_f32_e32 v47, v47
	v_sqrt_f32_e32 v61, v61
	s_waitcnt lgkmcnt(0)
	v_lshlrev_b32_e32 v155, 16, v53
	v_mul_f32_e32 v46, v46, v105
	v_and_b32_e32 v105, 0xffff0000, v52
	v_lshlrev_b32_e32 v52, 16, v52
	v_mul_f32_e32 v44, v44, v55
	v_mul_f32_e32 v46, v46, v155
	v_mul_f32_e32 v45, v45, v105
	v_mul_f32_e32 v44, v44, v52
	v_and_b32_e32 v52, 0xffff0000, v53
	v_mul_f32_e32 v47, v47, v61
	v_mul_f32_e32 v47, v47, v52
	s_nop 1
	v_cvt_pk_bf16_f32 v44, v44, v45
	s_nop 1
	v_cvt_pk_bf16_f32 v45, v46, v47
	v_add_u32_e32 v46, v113, v112
	ds_read_b64 v[46:47], v46
	s_nop 1
	v_cvt_pk_bf16_f32 v52, v54, v60
	v_lshlrev_b32_e32 v54, 16, v149
	v_mul_f32_e32 v54, v152, v54
	v_add_f32_e32 v60, v54, v54
	s_mov_b32 s0, 0xbca3d70a
	v_cmp_nlt_f32_e64 s[0:1], s0, v60
	s_nop 1
	v_cvt_pk_bf16_f32 v53, v62, v63
	s_and_saveexec_b64 s[2:3], s[0:1]
	s_xor_b64 s[0:1], exec, s[2:3]
	v_mul_f32_e32 v55, 0x3fb8aa3b, v60
	v_exp_f32_e32 v55, v55
	s_nop 0
	v_sub_f32_e32 v55, 1.0, v55
	s_andn2_saveexec_b64 s[0:1], s[0:1]
	s_mov_b32 s2, 0x3e2aaaab
	v_fma_f32 v55, v60, s2, 0.5
	v_fma_f32 v55, v60, v55, 1.0
	v_mul_f32_e64 v55, v55, -v60
	s_or_b64 exec, exec, s[0:1]
	v_and_b32_e32 v60, 0xffff0000, v149
	v_mul_f32_e32 v60, v153, v60
	v_add_f32_e32 v62, v60, v60
	s_mov_b32 s0, 0xbca3d70a
	v_cmp_nlt_f32_e64 s[0:1], s0, v62
	s_and_saveexec_b64 s[2:3], s[0:1]
	s_xor_b64 s[0:1], exec, s[2:3]
	v_mul_f32_e32 v61, 0x3fb8aa3b, v62
	v_exp_f32_e32 v61, v61
	s_nop 0
	v_sub_f32_e32 v61, 1.0, v61
	s_andn2_saveexec_b64 s[0:1], s[0:1]
	s_mov_b32 s2, 0x3e2aaaab
	v_fma_f32 v61, v62, s2, 0.5
	v_fma_f32 v61, v62, v61, 1.0
	v_mul_f32_e64 v61, v61, -v62
	s_or_b64 exec, exec, s[0:1]
	v_lshlrev_b32_e32 v62, 16, v148
	v_mul_f32_e32 v63, v151, v62
	v_add_f32_e32 v62, v63, v63
	s_mov_b32 s0, 0xbca3d70a
	v_cmp_nlt_f32_e64 s[0:1], s0, v62
	s_and_saveexec_b64 s[2:3], s[0:1]
	s_xor_b64 s[0:1], exec, s[2:3]
	v_mul_f32_e32 v62, 0x3fb8aa3b, v62
	v_exp_f32_e32 v62, v62
	s_nop 0
	v_sub_f32_e32 v149, 1.0, v62
	s_andn2_saveexec_b64 s[0:1], s[0:1]
	s_mov_b32 s2, 0x3e2aaaab
	v_fma_f32 v105, v62, s2, 0.5
	v_fma_f32 v105, v62, v105, 1.0
	v_mul_f32_e64 v149, v105, -v62
	s_or_b64 exec, exec, s[0:1]
	v_and_b32_e32 v62, 0xffff0000, v148
	v_mul_f32_e32 v62, v154, v62
	v_add_f32_e32 v148, v62, v62
	s_mov_b32 s0, 0xbca3d70a
	v_cmp_nlt_f32_e64 s[0:1], s0, v148
	s_and_saveexec_b64 s[2:3], s[0:1]
	s_xor_b64 s[0:1], exec, s[2:3]
	v_mul_f32_e32 v105, 0x3fb8aa3b, v148
	v_exp_f32_e32 v105, v105
	s_nop 0
	v_sub_f32_e32 v105, 1.0, v105
	s_andn2_saveexec_b64 s[0:1], s[0:1]
	s_mov_b32 s2, 0x3e2aaaab
	v_fma_f32 v105, v148, s2, 0.5
	v_fma_f32 v105, v148, v105, 1.0
	v_mul_f32_e64 v105, v105, -v148
	s_or_b64 exec, exec, s[0:1]
	v_add_f32_e32 v40, v40, v56
	v_mul_f32_e32 v40, 0xbfb8aa3b, v40
	v_exp_f32_e32 v40, v40
	v_add_f32_e32 v42, v42, v58
	v_add_f32_e32 v41, v41, v57
	v_max_f32_e32 v55, v55, v55
	v_mul_f32_e32 v42, 0xbfb8aa3b, v42
	v_add_f32_e32 v43, v43, v59
	v_mul_f32_e32 v41, 0xbfb8aa3b, v41
	v_add_f32_e32 v40, 1.0, v40
	v_max_f32_e32 v55, 0, v55
	v_exp_f32_e32 v42, v42
	v_mul_f32_e32 v43, 0xbfb8aa3b, v43
	v_exp_f32_e32 v41, v41
	v_rcp_f32_e32 v40, v40
	v_sqrt_f32_e32 v55, v55
	v_exp_f32_e32 v43, v43
	v_max_f32_e32 v148, v149, v149
	v_max_f32_e32 v61, v61, v61
	v_max_f32_e32 v148, 0, v148
	v_add_f32_e32 v42, 1.0, v42
	v_add_f32_e32 v41, 1.0, v41
	v_max_f32_e32 v61, 0, v61
	v_mul_f32_e32 v40, v40, v55
	v_max_f32_e32 v55, v105, v105
	v_sqrt_f32_e32 v148, v148
	v_rcp_f32_e32 v42, v42
	v_add_f32_e32 v43, 1.0, v43
	v_rcp_f32_e32 v41, v41
	v_sqrt_f32_e32 v61, v61
	v_max_f32_e32 v55, 0, v55
	v_rcp_f32_e32 v43, v43
	v_sqrt_f32_e32 v55, v55
	v_mul_f32_e32 v42, v42, v148
	s_waitcnt lgkmcnt(0)
	v_and_b32_e32 v148, 0xffff0000, v46
	v_mul_f32_e32 v41, v41, v61
	v_lshlrev_b32_e32 v46, 16, v46
	v_lshlrev_b32_e32 v149, 16, v47
	v_mul_f32_e32 v41, v41, v148
	v_cndmask_b32_e32 v60, v60, v218, vcc
	v_mul_f32_e32 v40, v40, v46
	v_cndmask_b32_e32 v46, v54, v218, vcc
	v_and_b32_e32 v47, 0xffff0000, v47
	v_mul_f32_e32 v43, v43, v55
	v_mul_f32_e32 v42, v42, v149
	v_mul_f32_e32 v43, v43, v47
	v_cndmask_b32_e32 v47, v62, v218, vcc
	s_nop 1
	v_cvt_pk_bf16_f32 v60, v46, v60
	s_nop 1
	v_cvt_pk_bf16_f32 v46, v40, v41
	ds_read_b64 v[40:41], v104 offset:4096
	v_cndmask_b32_e32 v63, v63, v218, vcc
	s_nop 1
	v_cvt_pk_bf16_f32 v61, v63, v47
	s_nop 1
	v_cvt_pk_bf16_f32 v47, v42, v43
	v_lshlrev_b32_e32 v42, 16, v147
	v_mul_f32_e32 v42, v152, v42
	v_add_f32_e32 v54, v42, v42
	s_mov_b32 s0, 0xbca3d70a
	v_cmp_nlt_f32_e64 s[0:1], s0, v54
	s_and_saveexec_b64 s[2:3], s[0:1]
	s_xor_b64 s[0:1], exec, s[2:3]
	v_mul_f32_e32 v43, 0x3fb8aa3b, v54
	v_exp_f32_e32 v43, v43
	s_nop 0
	v_sub_f32_e32 v43, 1.0, v43
	s_andn2_saveexec_b64 s[0:1], s[0:1]
	s_mov_b32 s2, 0x3e2aaaab
	v_fma_f32 v43, v54, s2, 0.5
	v_fma_f32 v43, v54, v43, 1.0
	v_mul_f32_e64 v43, v43, -v54
	s_or_b64 exec, exec, s[0:1]
	v_and_b32_e32 v54, 0xffff0000, v147
	v_mul_f32_e32 v54, v153, v54
	v_add_f32_e32 v55, v54, v54
	s_mov_b32 s0, 0xbca3d70a
	v_cmp_nlt_f32_e64 s[0:1], s0, v55
	s_and_saveexec_b64 s[2:3], s[0:1]
	s_xor_b64 s[0:1], exec, s[2:3]
	v_mul_f32_e32 v55, 0x3fb8aa3b, v55
	v_exp_f32_e32 v55, v55
	s_nop 0
	v_sub_f32_e32 v62, 1.0, v55
	s_andn2_saveexec_b64 s[0:1], s[0:1]
	s_mov_b32 s2, 0x3e2aaaab
	v_fma_f32 v62, v55, s2, 0.5
	v_fma_f32 v62, v55, v62, 1.0
	v_mul_f32_e64 v62, v62, -v55
	s_or_b64 exec, exec, s[0:1]
	v_lshlrev_b32_e32 v55, 16, v146
	v_mul_f32_e32 v55, v151, v55
	v_add_f32_e32 v63, v55, v55
	s_mov_b32 s0, 0xbca3d70a
	v_cmp_nlt_f32_e64 s[0:1], s0, v63
	s_and_saveexec_b64 s[2:3], s[0:1]
	s_xor_b64 s[0:1], exec, s[2:3]
	v_mul_f32_e32 v63, 0x3fb8aa3b, v63
	v_exp_f32_e32 v63, v63
	s_nop 0
	v_sub_f32_e32 v147, 1.0, v63
	s_andn2_saveexec_b64 s[0:1], s[0:1]
	s_mov_b32 s2, 0x3e2aaaab
	v_fma_f32 v105, v63, s2, 0.5
	v_fma_f32 v105, v63, v105, 1.0
	v_mul_f32_e64 v147, v105, -v63
	s_or_b64 exec, exec, s[0:1]
	v_and_b32_e32 v63, 0xffff0000, v146
	v_mul_f32_e32 v63, v154, v63
	v_add_f32_e32 v146, v63, v63
	s_mov_b32 s0, 0xbca3d70a
	v_cmp_nlt_f32_e64 s[0:1], s0, v146
	s_and_saveexec_b64 s[2:3], s[0:1]
	s_xor_b64 s[0:1], exec, s[2:3]
	v_mul_f32_e32 v105, 0x3fb8aa3b, v146
	v_exp_f32_e32 v105, v105
	s_nop 0
	v_sub_f32_e32 v105, 1.0, v105
	s_andn2_saveexec_b64 s[0:1], s[0:1]
	s_mov_b32 s2, 0x3e2aaaab
	v_fma_f32 v105, v146, s2, 0.5
	v_fma_f32 v105, v146, v105, 1.0
	v_mul_f32_e64 v105, v105, -v146
	s_or_b64 exec, exec, s[0:1]
	v_add_f32_e32 v37, v37, v57
	v_mul_f32_e32 v37, 0xbfb8aa3b, v37
	v_exp_f32_e32 v37, v37
	v_add_f32_e32 v38, v38, v58
	v_add_f32_e32 v36, v36, v56
	v_mul_f32_e32 v38, 0xbfb8aa3b, v38
	v_max_f32_e32 v62, v62, v62
	v_mul_f32_e32 v36, 0xbfb8aa3b, v36
	v_exp_f32_e32 v38, v38
	v_add_f32_e32 v39, v39, v59
	v_add_f32_e32 v37, 1.0, v37
	v_max_f32_e32 v62, 0, v62
	v_exp_f32_e32 v36, v36
	v_mul_f32_e32 v39, 0xbfb8aa3b, v39
	v_rcp_f32_e32 v37, v37
	v_sqrt_f32_e32 v62, v62
	v_exp_f32_e32 v39, v39
	v_max_f32_e32 v146, v147, v147
	v_max_f32_e32 v43, v43, v43
	v_max_f32_e32 v146, 0, v146
	v_add_f32_e32 v38, 1.0, v38
	v_add_f32_e32 v36, 1.0, v36
	v_max_f32_e32 v43, 0, v43
	v_sqrt_f32_e32 v146, v146
	v_rcp_f32_e32 v38, v38
	v_mul_f32_e32 v37, v37, v62
	v_rcp_f32_e32 v36, v36
	v_sqrt_f32_e32 v43, v43
	v_max_f32_e32 v62, v105, v105
	v_add_f32_e32 v39, 1.0, v39
	v_max_f32_e32 v62, 0, v62
	v_rcp_f32_e32 v39, v39
	v_sqrt_f32_e32 v62, v62
	v_mul_f32_e32 v38, v38, v146
	s_waitcnt lgkmcnt(0)
	v_and_b32_e32 v146, 0xffff0000, v40
	v_lshlrev_b32_e32 v40, 16, v40
	v_mul_f32_e32 v36, v36, v43
	v_mul_f32_e32 v36, v36, v40
	ds_read_b64 v[104:105], v104 offset:6144
	v_mul_f32_e32 v37, v37, v146
	v_mul_f32_e32 v39, v39, v62
	s_nop 1
	v_cvt_pk_bf16_f32 v62, v42, v54
	s_nop 1
	v_cvt_pk_bf16_f32 v54, v36, v37
	v_lshlrev_b32_e32 v36, 16, v145
	v_mul_f32_e32 v146, v152, v36
	v_add_f32_e32 v36, v146, v146
	s_mov_b32 s0, 0xbca3d70a
	v_lshlrev_b32_e32 v147, 16, v41
	v_and_b32_e32 v40, 0xffff0000, v41
	v_cmp_nlt_f32_e64 s[0:1], s0, v36
	v_mul_f32_e32 v38, v38, v147
	v_mul_f32_e32 v39, v39, v40
	s_nop 1
	v_cvt_pk_bf16_f32 v63, v55, v63
	s_nop 1
	v_cvt_pk_bf16_f32 v55, v38, v39
	s_and_saveexec_b64 s[2:3], s[0:1]
	s_xor_b64 s[0:1], exec, s[2:3]
	v_mul_f32_e32 v36, 0x3fb8aa3b, v36
	v_exp_f32_e32 v36, v36
	s_nop 0
	v_sub_f32_e32 v147, 1.0, v36
	s_andn2_saveexec_b64 s[0:1], s[0:1]
	s_mov_b32 s2, 0x3e2aaaab
	v_fma_f32 v37, v36, s2, 0.5
	v_fma_f32 v37, v36, v37, 1.0
	v_mul_f32_e64 v147, v37, -v36
	s_or_b64 exec, exec, s[0:1]
	v_and_b32_e32 v36, 0xffff0000, v145
	v_mul_f32_e32 v145, v153, v36
	v_add_f32_e32 v36, v145, v145
	s_mov_b32 s0, 0xbca3d70a
	v_cmp_nlt_f32_e64 s[0:1], s0, v36
	s_and_saveexec_b64 s[2:3], s[0:1]
	s_xor_b64 s[0:1], exec, s[2:3]
	v_mul_f32_e32 v36, 0x3fb8aa3b, v36
	v_exp_f32_e32 v36, v36
	s_nop 0
	v_sub_f32_e32 v148, 1.0, v36
	s_andn2_saveexec_b64 s[0:1], s[0:1]
	s_mov_b32 s2, 0x3e2aaaab
	v_fma_f32 v37, v36, s2, 0.5
	v_fma_f32 v37, v36, v37, 1.0
	v_mul_f32_e64 v148, v37, -v36
	s_or_b64 exec, exec, s[0:1]
	v_lshlrev_b32_e32 v36, 16, v144
	v_mul_f32_e32 v149, v151, v36
	v_add_f32_e32 v36, v149, v149
	s_mov_b32 s0, 0xbca3d70a
	v_cmp_nlt_f32_e64 s[0:1], s0, v36
	s_and_saveexec_b64 s[2:3], s[0:1]
	s_xor_b64 s[0:1], exec, s[2:3]
	v_mul_f32_e32 v36, 0x3fb8aa3b, v36
	v_exp_f32_e32 v36, v36
	s_nop 0
	v_sub_f32_e32 v150, 1.0, v36
	s_andn2_saveexec_b64 s[0:1], s[0:1]
	s_mov_b32 s2, 0x3e2aaaab
	v_fma_f32 v37, v36, s2, 0.5
	v_fma_f32 v37, v36, v37, 1.0
	v_mul_f32_e64 v150, v37, -v36
	s_or_b64 exec, exec, s[0:1]
	v_and_b32_e32 v36, 0xffff0000, v144
	v_mul_f32_e32 v144, v154, v36
	v_add_f32_e32 v36, v144, v144
	s_mov_b32 s0, 0xbca3d70a
	v_cmp_nlt_f32_e64 s[0:1], s0, v36
	s_and_saveexec_b64 s[2:3], s[0:1]
	s_xor_b64 s[0:1], exec, s[2:3]
	v_mul_f32_e32 v36, 0x3fb8aa3b, v36
	v_exp_f32_e32 v36, v36
	s_nop 0
	v_sub_f32_e32 v151, 1.0, v36
	s_andn2_saveexec_b64 s[0:1], s[0:1]
	s_mov_b32 s2, 0x3e2aaaab
	v_fma_f32 v37, v36, s2, 0.5
	v_fma_f32 v37, v36, v37, 1.0
	v_mul_f32_e64 v151, v37, -v36
	s_or_b64 exec, exec, s[0:1]
	global_load_dwordx4 v[40:43], v[100:101], off offset:128
	global_load_dwordx4 v[36:39], v[102:103], off offset:128
	v_add_f32_e32 v32, v32, v56
	v_mul_f32_e32 v32, 0xbfb8aa3b, v32
	v_exp_f32_e32 v32, v32
	v_add_f32_e32 v59, v35, v59
	v_add_f32_e32 v33, v33, v57
	v_max_f32_e32 v56, v147, v147
	v_add_f32_e32 v152, v34, v58
	v_max_f32_e32 v57, v148, v148
	v_mul_f32_e32 v59, 0xbfb8aa3b, v59
	v_mul_f32_e32 v33, 0xbfb8aa3b, v33
	v_max_f32_e32 v148, 0, v56
	v_add_f32_e32 v32, 1.0, v32
	s_nop 1
	v_cvt_pk_bf16_f32 v35, v149, v144
	v_mul_f32_e32 v144, 0xbfb8aa3b, v152
	v_exp_f32_e32 v59, v59
	v_exp_f32_e32 v33, v33
	v_sqrt_f32_e32 v148, v148
	v_rcp_f32_e32 v32, v32
	v_exp_f32_e32 v144, v144
	v_max_f32_e32 v147, v151, v151
	s_mov_b32 s0, 0x800000
	v_max_f32_e32 v150, v150, v150
	s_waitcnt lgkmcnt(0)
	v_and_b32_e32 v154, 0xffff0000, v104
	v_lshlrev_b32_e32 v104, 16, v104
	s_nop 1
	v_cvt_pk_bf16_f32 v34, v146, v145
	v_max_f32_e32 v146, 0, v57
	v_max_f32_e32 v147, 0, v147
	v_add_f32_e32 v59, 1.0, v59
	v_add_f32_e32 v33, 1.0, v33
	v_mul_f32_e32 v32, v32, v148
	v_max_f32_e32 v145, 0, v150
	v_sqrt_f32_e32 v146, v146
	v_sqrt_f32_e32 v147, v147
	v_add_f32_e32 v144, 1.0, v144
	v_rcp_f32_e32 v33, v33
	v_rcp_f32_e32 v59, v59
	v_mul_f32_e32 v32, v32, v104
	v_sqrt_f32_e32 v145, v145
	v_rcp_f32_e32 v144, v144
	v_lshlrev_b32_e32 v153, 16, v105
	v_and_b32_e32 v105, 0xffff0000, v105
	v_mul_f32_e32 v33, v33, v146
	v_mul_f32_e32 v59, v59, v147
	v_mul_f32_e32 v144, v144, v145
	v_mul_f32_e32 v33, v33, v154
	v_mul_f32_e32 v59, v59, v105
	v_mul_f32_e32 v144, v144, v153
	s_nop 1
	v_cvt_pk_bf16_f32 v32, v32, v33
	s_nop 1
	v_cvt_pk_bf16_f32 v33, v144, v59
	v_add_u32_e32 v58, v114, v110
	ds_read_b64 v[56:57], v58
	s_waitcnt vmcnt(1)
	v_mul_f32_e32 v40, 0xbfb8aa3b, v40
	v_exp_f32_e32 v40, v40
	s_nop 0
	v_add_f32_e32 v40, 1.0, v40
	v_cmp_gt_f32_e64 s[0:1], s0, v40
	s_nop 1
	v_cndmask_b32_e64 v104, 0, 32, s[0:1]
	v_ldexp_f32 v40, v40, v104
	v_log_f32_e32 v40, v40
	v_cndmask_b32_e64 v59, 0, v217, s[0:1]
	s_mov_b32 s0, 0x3f317217
	v_mul_f32_e32 v104, 0x3f317217, v40
	v_fma_f32 v104, v40, s0, -v104
	v_fmac_f32_e32 v104, 0x3377d1cf, v40
	s_mov_b32 s0, 0x7f800000
	v_fmac_f32_e32 v104, 0x3f317217, v40
	v_cmp_lt_f32_e64 s[0:1], |v40|, s0
	s_nop 1
	v_cndmask_b32_e64 v40, v40, v104, s[0:1]
	v_sub_f32_e32 v40, v40, v59
	v_mul_f32_e32 v59, 0xc1000000, v40
	v_lshlrev_b32_e32 v40, 16, v143
	v_mul_f32_e32 v40, v59, v40
	v_add_f32_e32 v104, v40, v40
	s_mov_b32 s0, 0xbca3d70a
	v_cmp_nlt_f32_e64 s[0:1], s0, v104
	s_and_saveexec_b64 s[2:3], s[0:1]
	s_xor_b64 s[0:1], exec, s[2:3]
	v_mul_f32_e32 v104, 0x3fb8aa3b, v104
	v_exp_f32_e32 v104, v104
	s_nop 0
	v_sub_f32_e32 v144, 1.0, v104
	s_andn2_saveexec_b64 s[0:1], s[0:1]
	s_mov_b32 s2, 0x3e2aaaab
	v_fma_f32 v105, v104, s2, 0.5
	v_fma_f32 v105, v104, v105, 1.0
	v_mul_f32_e64 v144, v105, -v104
	s_or_b64 exec, exec, s[0:1]
	v_mul_f32_e32 v41, 0xbfb8aa3b, v41
	v_exp_f32_e32 v41, v41
	s_mov_b32 s0, 0x800000
	v_add_f32_e32 v41, 1.0, v41
	v_cmp_gt_f32_e64 s[0:1], s0, v41
	s_nop 1
	v_cndmask_b32_e64 v104, 0, 32, s[0:1]
	v_ldexp_f32 v41, v41, v104
	v_log_f32_e32 v41, v41
	v_cndmask_b32_e64 v104, 0, v217, s[0:1]
	s_mov_b32 s0, 0x3f317217
	v_mul_f32_e32 v105, 0x3f317217, v41
	v_fma_f32 v105, v41, s0, -v105
	v_fmac_f32_e32 v105, 0x3377d1cf, v41
	s_mov_b32 s0, 0x7f800000
	v_fmac_f32_e32 v105, 0x3f317217, v41
	v_cmp_lt_f32_e64 s[0:1], |v41|, s0
	s_nop 1
	v_cndmask_b32_e64 v41, v41, v105, s[0:1]
	v_sub_f32_e32 v41, v41, v104
	v_mul_f32_e32 v104, 0xc1000000, v41
	v_and_b32_e32 v41, 0xffff0000, v143
	v_mul_f32_e32 v41, v104, v41
	v_add_f32_e32 v105, v41, v41
	s_mov_b32 s0, 0xbca3d70a
	v_cmp_nlt_f32_e64 s[0:1], s0, v105
	s_and_saveexec_b64 s[2:3], s[0:1]
	s_xor_b64 s[0:1], exec, s[2:3]
	v_mul_f32_e32 v105, 0x3fb8aa3b, v105
	v_exp_f32_e32 v105, v105
	s_nop 0
	v_sub_f32_e32 v145, 1.0, v105
	s_andn2_saveexec_b64 s[0:1], s[0:1]
	s_mov_b32 s2, 0x3e2aaaab
	v_fma_f32 v143, v105, s2, 0.5
	v_fma_f32 v143, v105, v143, 1.0
	v_mul_f32_e64 v145, v143, -v105
	s_or_b64 exec, exec, s[0:1]
	v_mul_f32_e32 v42, 0xbfb8aa3b, v42
	v_exp_f32_e32 v42, v42
	s_mov_b32 s0, 0x800000
	v_add_f32_e32 v42, 1.0, v42
	v_cmp_gt_f32_e64 s[0:1], s0, v42
	s_nop 1
	v_cndmask_b32_e64 v105, 0, 32, s[0:1]
	v_ldexp_f32 v42, v42, v105
	v_log_f32_e32 v42, v42
	v_cndmask_b32_e64 v105, 0, v217, s[0:1]
	s_mov_b32 s0, 0x3f317217
	v_mul_f32_e32 v143, 0x3f317217, v42
	v_fma_f32 v143, v42, s0, -v143
	v_fmac_f32_e32 v143, 0x3377d1cf, v42
	s_mov_b32 s0, 0x7f800000
	v_fmac_f32_e32 v143, 0x3f317217, v42
	v_cmp_lt_f32_e64 s[0:1], |v42|, s0
	s_nop 1
	v_cndmask_b32_e64 v42, v42, v143, s[0:1]
	v_sub_f32_e32 v42, v42, v105
	v_mul_f32_e32 v105, 0xc1000000, v42
	v_lshlrev_b32_e32 v42, 16, v142
	v_mul_f32_e32 v42, v105, v42
	v_add_f32_e32 v143, v42, v42
	s_mov_b32 s0, 0xbca3d70a
	v_cmp_nlt_f32_e64 s[0:1], s0, v143
	s_and_saveexec_b64 s[2:3], s[0:1]
	s_xor_b64 s[0:1], exec, s[2:3]
	v_mul_f32_e32 v143, 0x3fb8aa3b, v143
	v_exp_f32_e32 v143, v143
	s_nop 0
	v_sub_f32_e32 v146, 1.0, v143
	s_andn2_saveexec_b64 s[0:1], s[0:1]
	s_mov_b32 s2, 0x3e2aaaab
	v_fma_f32 v146, v143, s2, 0.5
	v_fma_f32 v146, v143, v146, 1.0
	v_mul_f32_e64 v146, v146, -v143
	s_or_b64 exec, exec, s[0:1]
	v_mul_f32_e32 v43, 0xbfb8aa3b, v43
	v_exp_f32_e32 v43, v43
	s_mov_b32 s0, 0x800000
	v_add_f32_e32 v43, 1.0, v43
	v_cmp_gt_f32_e64 s[0:1], s0, v43
	s_nop 1
	v_cndmask_b32_e64 v143, 0, 32, s[0:1]
	v_ldexp_f32 v43, v43, v143
	v_log_f32_e32 v43, v43
	v_cndmask_b32_e64 v143, 0, v217, s[0:1]
	s_mov_b32 s0, 0x3f317217
	v_mul_f32_e32 v147, 0x3f317217, v43
	v_fma_f32 v147, v43, s0, -v147
	v_fmac_f32_e32 v147, 0x3377d1cf, v43
	s_mov_b32 s0, 0x7f800000
	v_fmac_f32_e32 v147, 0x3f317217, v43
	v_cmp_lt_f32_e64 s[0:1], |v43|, s0
	s_nop 1
	v_cndmask_b32_e64 v43, v43, v147, s[0:1]
	v_sub_f32_e32 v43, v43, v143
	v_mul_f32_e32 v143, 0xc1000000, v43
	v_and_b32_e32 v43, 0xffff0000, v142
	v_mul_f32_e32 v43, v143, v43
	v_add_f32_e32 v147, v43, v43
	s_mov_b32 s0, 0xbca3d70a
	v_cmp_nlt_f32_e64 s[0:1], s0, v147
	s_and_saveexec_b64 s[2:3], s[0:1]
	s_xor_b64 s[0:1], exec, s[2:3]
	v_mul_f32_e32 v142, 0x3fb8aa3b, v147
	v_exp_f32_e32 v142, v142
	s_nop 0
	v_sub_f32_e32 v142, 1.0, v142
	s_andn2_saveexec_b64 s[0:1], s[0:1]
	s_mov_b32 s2, 0x3e2aaaab
	v_fma_f32 v142, v147, s2, 0.5
	v_fma_f32 v142, v147, v142, 1.0
	v_mul_f32_e64 v142, v142, -v147
	s_or_b64 exec, exec, s[0:1]
	s_waitcnt vmcnt(0)
	v_add_f32_e32 v30, v30, v38
	v_mul_f32_e32 v30, 0xbfb8aa3b, v30
	v_add_f32_e32 v29, v29, v37
	v_exp_f32_e32 v30, v30
	v_mul_f32_e32 v29, 0xbfb8aa3b, v29
	v_exp_f32_e32 v29, v29
	v_max_f32_e32 v146, v146, v146
	v_max_f32_e32 v146, 0, v146
	v_add_f32_e32 v30, 1.0, v30
	v_add_f32_e32 v31, v31, v39
	v_max_f32_e32 v145, v145, v145
	v_sqrt_f32_e32 v146, v146
	v_rcp_f32_e32 v30, v30
	v_mul_f32_e32 v31, 0xbfb8aa3b, v31
	v_add_f32_e32 v29, 1.0, v29
	v_max_f32_e32 v145, 0, v145
	v_exp_f32_e32 v31, v31
	v_rcp_f32_e32 v29, v29
	v_sqrt_f32_e32 v145, v145
	v_add_f32_e32 v28, v28, v36
	v_mul_f32_e32 v28, 0xbfb8aa3b, v28
	v_exp_f32_e32 v28, v28
	s_waitcnt lgkmcnt(0)
	v_lshlrev_b32_e32 v147, 16, v57
	v_mul_f32_e32 v30, v30, v146
	v_mul_f32_e32 v146, v30, v147
	v_add_f32_e32 v30, 1.0, v31
	v_and_b32_e32 v31, 0xffff0000, v56
	v_mul_f32_e32 v29, v29, v145
	v_mul_f32_e32 v29, v29, v31
	v_lshlrev_b32_e32 v31, 16, v56
	v_max_f32_e32 v56, v144, v144
	v_add_f32_e32 v28, 1.0, v28
	v_max_f32_e32 v56, 0, v56
	v_max_f32_e32 v142, v142, v142
	v_rcp_f32_e32 v28, v28
	v_sqrt_f32_e32 v56, v56
	v_max_f32_e32 v142, 0, v142
	v_rcp_f32_e32 v30, v30
	v_sqrt_f32_e32 v142, v142
	v_mul_f32_e32 v28, v28, v56
	v_mul_f32_e32 v28, v28, v31
	v_and_b32_e32 v31, 0xffff0000, v57
	v_mul_f32_e32 v30, v30, v142
	v_mul_f32_e32 v56, v30, v31
	s_nop 1
	v_cvt_pk_bf16_f32 v30, v40, v41
	v_add_u32_e32 v40, v114, v112
	ds_read_b64 v[40:41], v40
	s_nop 1
	v_cvt_pk_bf16_f32 v31, v42, v43
	v_lshlrev_b32_e32 v42, 16, v141
	v_mul_f32_e32 v42, v59, v42
	s_nop 1
	v_cvt_pk_bf16_f32 v28, v28, v29
	s_nop 1
	v_cvt_pk_bf16_f32 v29, v146, v56
	v_add_f32_e32 v56, v42, v42
	s_mov_b32 s0, 0xbca3d70a
	v_cmp_nlt_f32_e64 s[0:1], s0, v56
	s_and_saveexec_b64 s[2:3], s[0:1]
	s_xor_b64 s[0:1], exec, s[2:3]
	v_mul_f32_e32 v43, 0x3fb8aa3b, v56
	v_exp_f32_e32 v43, v43
	s_nop 0
	v_sub_f32_e32 v43, 1.0, v43
	s_andn2_saveexec_b64 s[0:1], s[0:1]
	s_mov_b32 s2, 0x3e2aaaab
	v_fma_f32 v43, v56, s2, 0.5
	v_fma_f32 v43, v56, v43, 1.0
	v_mul_f32_e64 v43, v43, -v56
	s_or_b64 exec, exec, s[0:1]
	v_and_b32_e32 v56, 0xffff0000, v141
	v_mul_f32_e32 v56, v104, v56
	v_add_f32_e32 v141, v56, v56
	s_mov_b32 s0, 0xbca3d70a
	v_cmp_nlt_f32_e64 s[0:1], s0, v141
	s_and_saveexec_b64 s[2:3], s[0:1]
	s_xor_b64 s[0:1], exec, s[2:3]
	v_mul_f32_e32 v57, 0x3fb8aa3b, v141
	v_exp_f32_e32 v57, v57
	s_nop 0
	v_sub_f32_e32 v57, 1.0, v57
	s_andn2_saveexec_b64 s[0:1], s[0:1]
	s_mov_b32 s2, 0x3e2aaaab
	v_fma_f32 v57, v141, s2, 0.5
	v_fma_f32 v57, v141, v57, 1.0
	v_mul_f32_e64 v57, v57, -v141
	s_or_b64 exec, exec, s[0:1]
	v_lshlrev_b32_e32 v141, 16, v140
	v_mul_f32_e32 v141, v105, v141
	v_add_f32_e32 v142, v141, v141
	s_mov_b32 s0, 0xbca3d70a
	v_cmp_nlt_f32_e64 s[0:1], s0, v142
	s_and_saveexec_b64 s[2:3], s[0:1]
	s_xor_b64 s[0:1], exec, s[2:3]
	v_mul_f32_e32 v142, 0x3fb8aa3b, v142
	v_exp_f32_e32 v142, v142
	s_nop 0
	v_sub_f32_e32 v144, 1.0, v142
	s_andn2_saveexec_b64 s[0:1], s[0:1]
	s_mov_b32 s2, 0x3e2aaaab
	v_fma_f32 v144, v142, s2, 0.5
	v_fma_f32 v144, v142, v144, 1.0
	v_mul_f32_e64 v144, v144, -v142
	s_or_b64 exec, exec, s[0:1]
	v_and_b32_e32 v140, 0xffff0000, v140
	v_mul_f32_e32 v140, v143, v140
	v_add_f32_e32 v145, v140, v140
	s_mov_b32 s0, 0xbca3d70a
	v_cmp_nlt_f32_e64 s[0:1], s0, v145
	s_and_saveexec_b64 s[2:3], s[0:1]
	s_xor_b64 s[0:1], exec, s[2:3]
	v_mul_f32_e32 v142, 0x3fb8aa3b, v145
	v_exp_f32_e32 v142, v142
	s_nop 0
	v_sub_f32_e32 v142, 1.0, v142
	s_andn2_saveexec_b64 s[0:1], s[0:1]
	s_mov_b32 s2, 0x3e2aaaab
	v_fma_f32 v142, v145, s2, 0.5
	v_fma_f32 v142, v145, v142, 1.0
	v_mul_f32_e64 v142, v142, -v145
	s_or_b64 exec, exec, s[0:1]
	v_add_f32_e32 v24, v24, v36
	v_mul_f32_e32 v24, 0xbfb8aa3b, v24
	v_exp_f32_e32 v24, v24
	v_max_f32_e32 v43, v43, v43
	v_add_f32_e32 v26, v26, v38
	v_add_f32_e32 v27, v27, v39
	v_add_f32_e32 v25, v25, v37
	v_add_f32_e32 v24, 1.0, v24
	v_max_f32_e32 v43, 0, v43
	v_mul_f32_e32 v26, 0xbfb8aa3b, v26
	v_mul_f32_e32 v27, 0xbfb8aa3b, v27
	v_mul_f32_e32 v25, 0xbfb8aa3b, v25
	v_rcp_f32_e32 v24, v24
	v_sqrt_f32_e32 v43, v43
	v_exp_f32_e32 v26, v26
	v_exp_f32_e32 v27, v27
	v_exp_f32_e32 v25, v25
	v_max_f32_e32 v144, v144, v144
	v_max_f32_e32 v57, v57, v57
	v_mul_f32_e32 v24, v24, v43
	v_max_f32_e32 v43, v142, v142
	v_max_f32_e32 v144, 0, v144
	v_add_f32_e32 v26, 1.0, v26
	v_add_f32_e32 v27, 1.0, v27
	v_add_f32_e32 v25, 1.0, v25
	v_max_f32_e32 v57, 0, v57
	v_max_f32_e32 v43, 0, v43
	v_sqrt_f32_e32 v144, v144
	v_rcp_f32_e32 v26, v26
	v_rcp_f32_e32 v25, v25
	v_sqrt_f32_e32 v57, v57
	v_rcp_f32_e32 v27, v27
	v_sqrt_f32_e32 v43, v43
	s_waitcnt lgkmcnt(0)
	v_lshlrev_b32_e32 v145, 16, v41
	v_mul_f32_e32 v26, v26, v144
	v_and_b32_e32 v144, 0xffff0000, v40
	v_mul_f32_e32 v25, v25, v57
	v_lshlrev_b32_e32 v40, 16, v40
	v_and_b32_e32 v41, 0xffff0000, v41
	v_mul_f32_e32 v27, v27, v43
	v_mul_f32_e32 v26, v26, v145
	v_mul_f32_e32 v25, v25, v144
	v_mul_f32_e32 v24, v24, v40
	v_mul_f32_e32 v27, v27, v41
	s_nop 1
	v_cvt_pk_bf16_f32 v24, v24, v25
	s_nop 1
	v_cvt_pk_bf16_f32 v25, v26, v27
	ds_read_b64 v[26:27], v58 offset:4096
	v_cndmask_b32_e32 v40, v42, v218, vcc
	v_lshlrev_b32_e32 v42, 16, v139
	v_cndmask_b32_e32 v56, v56, v218, vcc
	v_mul_f32_e32 v42, v59, v42
	s_nop 1
	v_cvt_pk_bf16_f32 v40, v40, v56
	v_add_f32_e32 v56, v42, v42
	s_mov_b32 s0, 0xbca3d70a
	v_cndmask_b32_e32 v41, v140, v218, vcc
	v_cmp_nlt_f32_e64 s[0:1], s0, v56
	v_cndmask_b32_e32 v141, v141, v218, vcc
	s_nop 1
	v_cvt_pk_bf16_f32 v41, v141, v41
	s_and_saveexec_b64 s[2:3], s[0:1]
	s_xor_b64 s[0:1], exec, s[2:3]
	v_mul_f32_e32 v43, 0x3fb8aa3b, v56
	v_exp_f32_e32 v43, v43
	s_nop 0
	v_sub_f32_e32 v43, 1.0, v43
	s_andn2_saveexec_b64 s[0:1], s[0:1]
	s_mov_b32 s2, 0x3e2aaaab
	v_fma_f32 v43, v56, s2, 0.5
	v_fma_f32 v43, v56, v43, 1.0
	v_mul_f32_e64 v43, v43, -v56
	s_or_b64 exec, exec, s[0:1]
	v_and_b32_e32 v56, 0xffff0000, v139
	v_mul_f32_e32 v56, v104, v56
	v_add_f32_e32 v57, v56, v56
	s_mov_b32 s0, 0xbca3d70a
	v_cmp_nlt_f32_e64 s[0:1], s0, v57
	s_and_saveexec_b64 s[2:3], s[0:1]
	s_xor_b64 s[0:1], exec, s[2:3]
	v_mul_f32_e32 v57, 0x3fb8aa3b, v57
	v_exp_f32_e32 v57, v57
	s_nop 0
	v_sub_f32_e32 v139, 1.0, v57
	s_andn2_saveexec_b64 s[0:1], s[0:1]
	s_mov_b32 s2, 0x3e2aaaab
	v_fma_f32 v139, v57, s2, 0.5
	v_fma_f32 v139, v57, v139, 1.0
	v_mul_f32_e64 v139, v139, -v57
	s_or_b64 exec, exec, s[0:1]
	v_lshlrev_b32_e32 v57, 16, v138
	v_mul_f32_e32 v57, v105, v57
	v_add_f32_e32 v140, v57, v57
	s_mov_b32 s0, 0xbca3d70a
	v_cmp_nlt_f32_e64 s[0:1], s0, v140
	s_and_saveexec_b64 s[2:3], s[0:1]
	s_xor_b64 s[0:1], exec, s[2:3]
	v_mul_f32_e32 v140, 0x3fb8aa3b, v140
	v_exp_f32_e32 v140, v140
	s_nop 0
	v_sub_f32_e32 v141, 1.0, v140
	s_andn2_saveexec_b64 s[0:1], s[0:1]
	s_mov_b32 s2, 0x3e2aaaab
	v_fma_f32 v141, v140, s2, 0.5
	v_fma_f32 v141, v140, v141, 1.0
	v_mul_f32_e64 v141, v141, -v140
	s_or_b64 exec, exec, s[0:1]
	v_and_b32_e32 v138, 0xffff0000, v138
	v_mul_f32_e32 v138, v143, v138
	v_add_f32_e32 v142, v138, v138
	s_mov_b32 s0, 0xbca3d70a
	v_cmp_nlt_f32_e64 s[0:1], s0, v142
	s_and_saveexec_b64 s[2:3], s[0:1]
	s_xor_b64 s[0:1], exec, s[2:3]
	v_mul_f32_e32 v140, 0x3fb8aa3b, v142
	v_exp_f32_e32 v140, v140
	s_nop 0
	v_sub_f32_e32 v140, 1.0, v140
	s_andn2_saveexec_b64 s[0:1], s[0:1]
	s_mov_b32 s2, 0x3e2aaaab
	v_fma_f32 v140, v142, s2, 0.5
	v_fma_f32 v140, v142, v140, 1.0
	v_mul_f32_e64 v140, v140, -v142
	s_or_b64 exec, exec, s[0:1]
	v_add_f32_e32 v21, v21, v37
	v_mul_f32_e32 v21, 0xbfb8aa3b, v21
	v_exp_f32_e32 v21, v21
	v_add_f32_e32 v22, v22, v38
	v_max_f32_e32 v139, v139, v139
	v_add_f32_e32 v20, v20, v36
	v_mul_f32_e32 v22, 0xbfb8aa3b, v22
	v_add_f32_e32 v23, v23, v39
	v_add_f32_e32 v21, 1.0, v21
	v_max_f32_e32 v139, 0, v139
	v_mul_f32_e32 v20, 0xbfb8aa3b, v20
	v_exp_f32_e32 v22, v22
	v_mul_f32_e32 v23, 0xbfb8aa3b, v23
	v_rcp_f32_e32 v21, v21
	v_sqrt_f32_e32 v139, v139
	v_exp_f32_e32 v20, v20
	v_exp_f32_e32 v23, v23
	v_max_f32_e32 v141, v141, v141
	v_max_f32_e32 v43, v43, v43
	v_max_f32_e32 v141, 0, v141
	v_add_f32_e32 v22, 1.0, v22
	v_mul_f32_e32 v21, v21, v139
	v_add_f32_e32 v20, 1.0, v20
	v_max_f32_e32 v43, 0, v43
	v_max_f32_e32 v139, v140, v140
	v_sqrt_f32_e32 v141, v141
	v_rcp_f32_e32 v22, v22
	v_add_f32_e32 v23, 1.0, v23
	v_rcp_f32_e32 v20, v20
	v_sqrt_f32_e32 v43, v43
	v_max_f32_e32 v139, 0, v139
	v_rcp_f32_e32 v23, v23
	v_sqrt_f32_e32 v139, v139
	v_mul_f32_e32 v22, v22, v141
	s_waitcnt lgkmcnt(0)
	v_and_b32_e32 v141, 0xffff0000, v26
	v_lshlrev_b32_e32 v26, 16, v26
	v_mul_f32_e32 v20, v20, v43
	v_lshlrev_b32_e32 v142, 16, v27
	v_mul_f32_e32 v21, v21, v141
	v_mul_f32_e32 v20, v20, v26
	v_and_b32_e32 v26, 0xffff0000, v27
	v_mul_f32_e32 v23, v23, v139
	v_mul_f32_e32 v22, v22, v142
	v_mul_f32_e32 v23, v23, v26
	s_nop 1
	v_cvt_pk_bf16_f32 v26, v20, v21
	ds_read_b64 v[20:21], v58 offset:6144
	s_nop 1
	v_cvt_pk_bf16_f32 v27, v22, v23
	v_lshlrev_b32_e32 v22, 16, v137
	v_mul_f32_e32 v22, v59, v22
	s_nop 1
	v_cvt_pk_bf16_f32 v42, v42, v56
	v_add_f32_e32 v56, v22, v22
	s_mov_b32 s0, 0xbca3d70a
	v_cmp_nlt_f32_e64 s[0:1], s0, v56
	s_nop 1
	v_cvt_pk_bf16_f32 v43, v57, v138
	s_and_saveexec_b64 s[2:3], s[0:1]
	s_xor_b64 s[0:1], exec, s[2:3]
	v_mul_f32_e32 v23, 0x3fb8aa3b, v56
	v_exp_f32_e32 v23, v23
	s_nop 0
	v_sub_f32_e32 v23, 1.0, v23
	s_andn2_saveexec_b64 s[0:1], s[0:1]
	s_mov_b32 s2, 0x3e2aaaab
	v_fma_f32 v23, v56, s2, 0.5
	v_fma_f32 v23, v56, v23, 1.0
	v_mul_f32_e64 v23, v23, -v56
	s_or_b64 exec, exec, s[0:1]
	v_and_b32_e32 v56, 0xffff0000, v137
	v_mul_f32_e32 v56, v104, v56
	v_add_f32_e32 v58, v56, v56
	s_mov_b32 s0, 0xbca3d70a
	v_cmp_nlt_f32_e64 s[0:1], s0, v58
	s_and_saveexec_b64 s[2:3], s[0:1]
	s_xor_b64 s[0:1], exec, s[2:3]
	v_mul_f32_e32 v57, 0x3fb8aa3b, v58
	v_exp_f32_e32 v57, v57
	s_nop 0
	v_sub_f32_e32 v57, 1.0, v57
	s_andn2_saveexec_b64 s[0:1], s[0:1]
	s_mov_b32 s2, 0x3e2aaaab
	v_fma_f32 v57, v58, s2, 0.5
	v_fma_f32 v57, v58, v57, 1.0
	v_mul_f32_e64 v57, v57, -v58
	s_or_b64 exec, exec, s[0:1]
	v_lshlrev_b32_e32 v58, 16, v136
	v_mul_f32_e32 v58, v105, v58
	v_add_f32_e32 v59, v58, v58
	s_mov_b32 s0, 0xbca3d70a
	v_cmp_nlt_f32_e64 s[0:1], s0, v59
	s_and_saveexec_b64 s[2:3], s[0:1]
	s_xor_b64 s[0:1], exec, s[2:3]
	v_mul_f32_e32 v59, 0x3fb8aa3b, v59
	v_exp_f32_e32 v59, v59
	s_nop 0
	v_sub_f32_e32 v104, 1.0, v59
	s_andn2_saveexec_b64 s[0:1], s[0:1]
	s_mov_b32 s2, 0x3e2aaaab
	v_fma_f32 v104, v59, s2, 0.5
	v_fma_f32 v104, v59, v104, 1.0
	v_mul_f32_e64 v104, v104, -v59
	s_or_b64 exec, exec, s[0:1]
	v_and_b32_e32 v59, 0xffff0000, v136
	v_mul_f32_e32 v59, v143, v59
	v_add_f32_e32 v136, v59, v59
	s_mov_b32 s0, 0xbca3d70a
	v_cmp_nlt_f32_e64 s[0:1], s0, v136
	s_and_saveexec_b64 s[2:3], s[0:1]
	s_xor_b64 s[0:1], exec, s[2:3]
	v_mul_f32_e32 v105, 0x3fb8aa3b, v136
	v_exp_f32_e32 v105, v105
	s_nop 0
	v_sub_f32_e32 v105, 1.0, v105
	s_andn2_saveexec_b64 s[0:1], s[0:1]
	s_mov_b32 s2, 0x3e2aaaab
	v_fma_f32 v105, v136, s2, 0.5
	v_fma_f32 v105, v136, v105, 1.0
	v_mul_f32_e64 v105, v105, -v136
	s_or_b64 exec, exec, s[0:1]
	v_add_f32_e32 v18, v18, v38
	v_add_f32_e32 v16, v16, v36
	v_mul_f32_e32 v18, 0xbfb8aa3b, v18
	v_mul_f32_e32 v16, 0xbfb8aa3b, v16
	v_exp_f32_e32 v18, v18
	v_exp_f32_e32 v16, v16
	v_max_f32_e32 v104, v104, v104
	v_max_f32_e32 v23, v23, v23
	v_add_f32_e32 v18, 1.0, v18
	v_max_f32_e32 v104, 0, v104
	v_add_f32_e32 v16, 1.0, v16
	v_max_f32_e32 v23, 0, v23
	v_rcp_f32_e32 v18, v18
	v_sqrt_f32_e32 v104, v104
	v_add_f32_e32 v19, v19, v39
	v_add_f32_e32 v17, v17, v37
	v_rcp_f32_e32 v16, v16
	v_sqrt_f32_e32 v23, v23
	v_mul_f32_e32 v19, 0xbfb8aa3b, v19
	v_mul_f32_e32 v17, 0xbfb8aa3b, v17
	v_exp_f32_e32 v19, v19
	v_exp_f32_e32 v17, v17
	s_waitcnt lgkmcnt(0)
	v_lshlrev_b32_e32 v38, 16, v21
	v_mul_f32_e32 v18, v18, v104
	v_and_b32_e32 v37, 0xffff0000, v20
	v_lshlrev_b32_e32 v20, 16, v20
	v_mul_f32_e32 v16, v16, v23
	v_mul_f32_e32 v18, v18, v38
	v_max_f32_e32 v38, v57, v57
	v_mul_f32_e32 v16, v16, v20
	v_and_b32_e32 v20, 0xffff0000, v21
	v_max_f32_e32 v21, v105, v105
	v_add_f32_e32 v19, 1.0, v19
	v_add_f32_e32 v17, 1.0, v17
	v_max_f32_e32 v38, 0, v38
	v_max_f32_e32 v21, 0, v21
	v_rcp_f32_e32 v19, v19
	v_rcp_f32_e32 v17, v17
	v_sqrt_f32_e32 v38, v38
	v_sqrt_f32_e32 v21, v21
	s_mov_b32 s0, 0x800000
	s_mov_b32 s2, 0x3f317217
	v_mul_f32_e32 v17, v17, v38
	v_mul_f32_e32 v19, v19, v21
	v_mul_f32_e32 v17, v17, v37
	v_mul_f32_e32 v19, v19, v20
	s_nop 1
	v_cvt_pk_bf16_f32 v38, v22, v56
	s_nop 1
	v_cvt_pk_bf16_f32 v36, v16, v17
	s_nop 1
	v_cvt_pk_bf16_f32 v37, v18, v19
	global_load_dwordx4 v[16:19], v[102:103], off offset:192
	global_load_dwordx4 v[20:23], v[100:101], off offset:192
	s_nop 1
	v_cvt_pk_bf16_f32 v39, v58, v59
	v_add_u32_e32 v59, v115, v110
	s_waitcnt vmcnt(0)
	v_mul_f32_e32 v20, 0xbfb8aa3b, v20
	v_exp_f32_e32 v20, v20
	s_nop 0
	v_add_f32_e32 v20, 1.0, v20
	v_cmp_gt_f32_e64 s[0:1], s0, v20
	s_nop 1
	v_cndmask_b32_e64 v56, 0, 32, s[0:1]
	v_ldexp_f32 v20, v20, v56
	v_log_f32_e32 v20, v20
	s_nop 0
	v_mul_f32_e32 v56, 0x3f317217, v20
	v_fma_f32 v56, v20, s2, -v56
	v_fmac_f32_e32 v56, 0x3377d1cf, v20
	s_mov_b32 s2, 0x7f800000
	v_fmac_f32_e32 v56, 0x3f317217, v20
	v_cmp_lt_f32_e64 s[4:5], |v20|, s2
	s_nop 1
	v_cndmask_b32_e64 v20, v20, v56, s[4:5]
	v_cndmask_b32_e64 v56, 0, v217, s[0:1]
	v_sub_f32_e32 v20, v20, v56
	ds_read_b64 v[56:57], v59
	v_mul_f32_e32 v58, 0xc1000000, v20
	v_lshlrev_b32_e32 v20, 16, v135
	v_mul_f32_e32 v20, v58, v20
	v_add_f32_e32 v100, v20, v20
	s_mov_b32 s0, 0xbca3d70a
	v_cmp_nlt_f32_e64 s[0:1], s0, v100
	s_and_saveexec_b64 s[2:3], s[0:1]
	s_xor_b64 s[0:1], exec, s[2:3]
	v_mul_f32_e32 v100, 0x3fb8aa3b, v100
	v_exp_f32_e32 v100, v100
	s_nop 0
	v_sub_f32_e32 v101, 1.0, v100
	s_andn2_saveexec_b64 s[0:1], s[0:1]
	s_mov_b32 s2, 0x3e2aaaab
	v_fma_f32 v101, v100, s2, 0.5
	v_fma_f32 v101, v100, v101, 1.0
	v_mul_f32_e64 v101, v101, -v100
	s_or_b64 exec, exec, s[0:1]
	v_mul_f32_e32 v21, 0xbfb8aa3b, v21
	v_exp_f32_e32 v21, v21
	s_mov_b32 s0, 0x800000
	v_add_f32_e32 v21, 1.0, v21
	v_cmp_gt_f32_e64 s[0:1], s0, v21
	s_nop 1
	v_cndmask_b32_e64 v100, 0, 32, s[0:1]
	v_ldexp_f32 v21, v21, v100
	v_log_f32_e32 v21, v21
	v_cndmask_b32_e64 v100, 0, v217, s[0:1]
	s_mov_b32 s0, 0x3f317217
	v_mul_f32_e32 v102, 0x3f317217, v21
	v_fma_f32 v102, v21, s0, -v102
	v_fmac_f32_e32 v102, 0x3377d1cf, v21
	s_mov_b32 s0, 0x7f800000
	v_fmac_f32_e32 v102, 0x3f317217, v21
	v_cmp_lt_f32_e64 s[0:1], |v21|, s0
	s_nop 1
	v_cndmask_b32_e64 v21, v21, v102, s[0:1]
	v_sub_f32_e32 v21, v21, v100
	v_mul_f32_e32 v100, 0xc1000000, v21
	v_and_b32_e32 v21, 0xffff0000, v135
	v_mul_f32_e32 v21, v100, v21
	v_add_f32_e32 v103, v21, v21
	s_mov_b32 s0, 0xbca3d70a
	v_cmp_nlt_f32_e64 s[0:1], s0, v103
	s_and_saveexec_b64 s[2:3], s[0:1]
	s_xor_b64 s[0:1], exec, s[2:3]
	v_mul_f32_e32 v102, 0x3fb8aa3b, v103
	v_exp_f32_e32 v102, v102
	s_nop 0
	v_sub_f32_e32 v102, 1.0, v102
	s_andn2_saveexec_b64 s[0:1], s[0:1]
	s_mov_b32 s2, 0x3e2aaaab
	v_fma_f32 v102, v103, s2, 0.5
	v_fma_f32 v102, v103, v102, 1.0
	v_mul_f32_e64 v102, v102, -v103
	s_or_b64 exec, exec, s[0:1]
	v_mul_f32_e32 v22, 0xbfb8aa3b, v22
	v_exp_f32_e32 v22, v22
	s_mov_b32 s0, 0x800000
	v_add_f32_e32 v22, 1.0, v22
	v_cmp_gt_f32_e64 s[0:1], s0, v22
	s_nop 1
	v_cndmask_b32_e64 v103, 0, 32, s[0:1]
	v_ldexp_f32 v22, v22, v103
	v_log_f32_e32 v22, v22
	v_cndmask_b32_e64 v103, 0, v217, s[0:1]
	s_mov_b32 s0, 0x3f317217
	v_mul_f32_e32 v104, 0x3f317217, v22
	v_fma_f32 v104, v22, s0, -v104
	v_fmac_f32_e32 v104, 0x3377d1cf, v22
	s_mov_b32 s0, 0x7f800000
	v_fmac_f32_e32 v104, 0x3f317217, v22
	v_cmp_lt_f32_e64 s[0:1], |v22|, s0
	s_nop 1
	v_cndmask_b32_e64 v22, v22, v104, s[0:1]
	v_sub_f32_e32 v22, v22, v103
	v_mul_f32_e32 v22, 0xc1000000, v22
	v_lshlrev_b32_e32 v103, 16, v134
	v_mul_f32_e32 v103, v22, v103
	v_add_f32_e32 v105, v103, v103
	s_mov_b32 s0, 0xbca3d70a
	v_cmp_nlt_f32_e64 s[0:1], s0, v105
	s_and_saveexec_b64 s[2:3], s[0:1]
	s_xor_b64 s[0:1], exec, s[2:3]
	v_mul_f32_e32 v104, 0x3fb8aa3b, v105
	v_exp_f32_e32 v104, v104
	s_nop 0
	v_sub_f32_e32 v104, 1.0, v104
	s_andn2_saveexec_b64 s[0:1], s[0:1]
	s_mov_b32 s2, 0x3e2aaaab
	v_fma_f32 v104, v105, s2, 0.5
	v_fma_f32 v104, v105, v104, 1.0
	v_mul_f32_e64 v104, v104, -v105
	s_or_b64 exec, exec, s[0:1]
	v_mul_f32_e32 v23, 0xbfb8aa3b, v23
	v_exp_f32_e32 v23, v23
	s_mov_b32 s0, 0x800000
	v_add_f32_e32 v23, 1.0, v23
	v_cmp_gt_f32_e64 s[0:1], s0, v23
	s_nop 1
	v_cndmask_b32_e64 v105, 0, 32, s[0:1]
	v_ldexp_f32 v23, v23, v105
	v_log_f32_e32 v23, v23
	v_cndmask_b32_e64 v105, 0, v217, s[0:1]
	s_mov_b32 s0, 0x3f317217
	v_mul_f32_e32 v135, 0x3f317217, v23
	v_fma_f32 v135, v23, s0, -v135
	v_fmac_f32_e32 v135, 0x3377d1cf, v23
	s_mov_b32 s0, 0x7f800000
	v_fmac_f32_e32 v135, 0x3f317217, v23
	v_cmp_lt_f32_e64 s[0:1], |v23|, s0
	s_nop 1
	v_cndmask_b32_e64 v23, v23, v135, s[0:1]
	v_sub_f32_e32 v23, v23, v105
	v_mul_f32_e32 v23, 0xc1000000, v23
	v_and_b32_e32 v105, 0xffff0000, v134
	v_mul_f32_e32 v105, v23, v105
	v_add_f32_e32 v135, v105, v105
	s_mov_b32 s0, 0xbca3d70a
	v_cmp_nlt_f32_e64 s[0:1], s0, v135
	s_and_saveexec_b64 s[2:3], s[0:1]
	s_xor_b64 s[0:1], exec, s[2:3]
	v_mul_f32_e32 v134, 0x3fb8aa3b, v135
	v_exp_f32_e32 v134, v134
	s_nop 0
	v_sub_f32_e32 v134, 1.0, v134
	s_andn2_saveexec_b64 s[0:1], s[0:1]
	s_mov_b32 s2, 0x3e2aaaab
	v_fma_f32 v134, v135, s2, 0.5
	v_fma_f32 v134, v135, v134, 1.0
	v_mul_f32_e64 v134, v134, -v135
	s_or_b64 exec, exec, s[0:1]
	v_add_f32_e32 v14, v14, v18
	v_mul_f32_e32 v14, 0xbfb8aa3b, v14
	v_add_f32_e32 v13, v13, v17
	v_exp_f32_e32 v14, v14
	v_mul_f32_e32 v13, 0xbfb8aa3b, v13
	v_exp_f32_e32 v13, v13
	v_max_f32_e32 v104, v104, v104
	v_max_f32_e32 v104, 0, v104
	v_add_f32_e32 v14, 1.0, v14
	v_add_f32_e32 v15, v15, v19
	v_max_f32_e32 v102, v102, v102
	v_sqrt_f32_e32 v104, v104
	v_rcp_f32_e32 v14, v14
	v_mul_f32_e32 v15, 0xbfb8aa3b, v15
	v_add_f32_e32 v13, 1.0, v13
	v_max_f32_e32 v102, 0, v102
	v_exp_f32_e32 v15, v15
	v_rcp_f32_e32 v13, v13
	v_sqrt_f32_e32 v102, v102
	v_add_f32_e32 v12, v12, v16
	v_mul_f32_e32 v12, 0xbfb8aa3b, v12
	v_exp_f32_e32 v12, v12
	s_waitcnt lgkmcnt(0)
	v_lshlrev_b32_e32 v135, 16, v57
	v_mul_f32_e32 v14, v14, v104
	v_mul_f32_e32 v104, v14, v135
	v_add_f32_e32 v14, 1.0, v15
	v_and_b32_e32 v15, 0xffff0000, v56
	v_mul_f32_e32 v13, v13, v102
	v_mul_f32_e32 v13, v13, v15
	v_lshlrev_b32_e32 v15, 16, v56
	v_max_f32_e32 v56, v101, v101
	v_add_f32_e32 v12, 1.0, v12
	v_max_f32_e32 v56, 0, v56
	v_max_f32_e32 v101, v134, v134
	v_rcp_f32_e32 v12, v12
	v_sqrt_f32_e32 v56, v56
	v_max_f32_e32 v101, 0, v101
	v_rcp_f32_e32 v14, v14
	v_sqrt_f32_e32 v101, v101
	v_mul_f32_e32 v12, v12, v56
	v_mul_f32_e32 v12, v12, v15
	v_and_b32_e32 v15, 0xffff0000, v57
	v_mul_f32_e32 v14, v14, v101
	v_mul_f32_e32 v56, v14, v15
	s_nop 1
	v_cvt_pk_bf16_f32 v14, v20, v21
	v_add_u32_e32 v20, v115, v112
	ds_read_b64 v[20:21], v20
	s_nop 1
	v_cvt_pk_bf16_f32 v12, v12, v13
	s_nop 1
	v_cvt_pk_bf16_f32 v13, v104, v56
	v_lshlrev_b32_e32 v56, 16, v133
	v_mul_f32_e32 v56, v58, v56
	v_add_f32_e32 v101, v56, v56
	s_mov_b32 s0, 0xbca3d70a
	v_cmp_nlt_f32_e64 s[0:1], s0, v101
	s_nop 1
	v_cvt_pk_bf16_f32 v15, v103, v105
	s_and_saveexec_b64 s[2:3], s[0:1]
	s_xor_b64 s[0:1], exec, s[2:3]
	v_mul_f32_e32 v57, 0x3fb8aa3b, v101
	v_exp_f32_e32 v57, v57
	s_nop 0
	v_sub_f32_e32 v57, 1.0, v57
	s_andn2_saveexec_b64 s[0:1], s[0:1]
	s_mov_b32 s2, 0x3e2aaaab
	v_fma_f32 v57, v101, s2, 0.5
	v_fma_f32 v57, v101, v57, 1.0
	v_mul_f32_e64 v57, v57, -v101
	s_or_b64 exec, exec, s[0:1]
	v_and_b32_e32 v101, 0xffff0000, v133
	v_mul_f32_e32 v101, v100, v101
	v_add_f32_e32 v103, v101, v101
	s_mov_b32 s0, 0xbca3d70a
	v_cmp_nlt_f32_e64 s[0:1], s0, v103
	s_and_saveexec_b64 s[2:3], s[0:1]
	s_xor_b64 s[0:1], exec, s[2:3]
	v_mul_f32_e32 v102, 0x3fb8aa3b, v103
	v_exp_f32_e32 v102, v102
	s_nop 0
	v_sub_f32_e32 v102, 1.0, v102
	s_andn2_saveexec_b64 s[0:1], s[0:1]
	s_mov_b32 s2, 0x3e2aaaab
	v_fma_f32 v102, v103, s2, 0.5
	v_fma_f32 v102, v103, v102, 1.0
	v_mul_f32_e64 v102, v102, -v103
	s_or_b64 exec, exec, s[0:1]
	v_lshlrev_b32_e32 v103, 16, v132
	v_mul_f32_e32 v104, v22, v103
	v_add_f32_e32 v103, v104, v104
	s_mov_b32 s0, 0xbca3d70a
	v_cmp_nlt_f32_e64 s[0:1], s0, v103
	s_and_saveexec_b64 s[2:3], s[0:1]
	s_xor_b64 s[0:1], exec, s[2:3]
	v_mul_f32_e32 v103, 0x3fb8aa3b, v103
	v_exp_f32_e32 v103, v103
	s_nop 0
	v_sub_f32_e32 v133, 1.0, v103
	s_andn2_saveexec_b64 s[0:1], s[0:1]
	s_mov_b32 s2, 0x3e2aaaab
	v_fma_f32 v105, v103, s2, 0.5
	v_fma_f32 v105, v103, v105, 1.0
	v_mul_f32_e64 v133, v105, -v103
	s_or_b64 exec, exec, s[0:1]
	v_and_b32_e32 v103, 0xffff0000, v132
	v_mul_f32_e32 v103, v23, v103
	v_add_f32_e32 v132, v103, v103
	s_mov_b32 s0, 0xbca3d70a
	v_cmp_nlt_f32_e64 s[0:1], s0, v132
	s_and_saveexec_b64 s[2:3], s[0:1]
	s_xor_b64 s[0:1], exec, s[2:3]
	v_mul_f32_e32 v105, 0x3fb8aa3b, v132
	v_exp_f32_e32 v105, v105
	s_nop 0
	v_sub_f32_e32 v105, 1.0, v105
	s_andn2_saveexec_b64 s[0:1], s[0:1]
	s_mov_b32 s2, 0x3e2aaaab
	v_fma_f32 v105, v132, s2, 0.5
	v_fma_f32 v105, v132, v105, 1.0
	v_mul_f32_e64 v105, v105, -v132
	s_or_b64 exec, exec, s[0:1]
	v_add_f32_e32 v10, v10, v18
	v_mul_f32_e32 v10, 0xbfb8aa3b, v10
	v_exp_f32_e32 v10, v10
	v_max_f32_e32 v132, v133, v133
	v_max_f32_e32 v132, 0, v132
	v_add_f32_e32 v11, v11, v19
	v_add_f32_e32 v10, 1.0, v10
	v_sqrt_f32_e32 v132, v132
	v_rcp_f32_e32 v10, v10
	v_mul_f32_e32 v11, 0xbfb8aa3b, v11
	v_add_f32_e32 v9, v9, v17
	v_exp_f32_e32 v11, v11
	v_mul_f32_e32 v9, 0xbfb8aa3b, v9
	v_exp_f32_e32 v9, v9
	s_waitcnt lgkmcnt(0)
	v_lshlrev_b32_e32 v133, 16, v21
	v_mul_f32_e32 v10, v10, v132
	v_mul_f32_e32 v132, v10, v133
	v_add_f32_e32 v10, 1.0, v11
	v_max_f32_e32 v11, v102, v102
	v_add_f32_e32 v9, 1.0, v9
	v_max_f32_e32 v11, 0, v11
	v_add_f32_e32 v8, v8, v16
	v_rcp_f32_e32 v9, v9
	v_sqrt_f32_e32 v11, v11
	v_mul_f32_e32 v8, 0xbfb8aa3b, v8
	v_exp_f32_e32 v8, v8
	v_rcp_f32_e32 v10, v10
	v_mul_f32_e32 v9, v9, v11
	v_max_f32_e32 v11, v57, v57
	v_add_f32_e32 v8, 1.0, v8
	v_max_f32_e32 v11, 0, v11
	v_rcp_f32_e32 v8, v8
	v_sqrt_f32_e32 v11, v11
	v_and_b32_e32 v102, 0xffff0000, v20
	v_lshlrev_b32_e32 v20, 16, v20
	v_and_b32_e32 v21, 0xffff0000, v21
	v_mul_f32_e32 v8, v8, v11
	v_max_f32_e32 v11, v105, v105
	v_max_f32_e32 v11, 0, v11
	v_sqrt_f32_e32 v11, v11
	v_mul_f32_e32 v9, v9, v102
	v_mul_f32_e32 v8, v8, v20
	v_cndmask_b32_e32 v20, v56, v218, vcc
	v_mul_f32_e32 v10, v10, v11
	v_mul_f32_e32 v21, v10, v21
	v_cndmask_b32_e32 v57, v101, v218, vcc
	s_nop 1
	v_cvt_pk_bf16_f32 v10, v20, v57
	s_nop 1
	v_cvt_pk_bf16_f32 v8, v8, v9
	s_nop 1
	v_cvt_pk_bf16_f32 v9, v132, v21
	ds_read_b64 v[20:21], v59 offset:4096
	v_lshlrev_b32_e32 v56, 16, v131
	v_mul_f32_e32 v56, v58, v56
	v_add_f32_e32 v101, v56, v56
	s_mov_b32 s0, 0xbca3d70a
	v_cndmask_b32_e32 v104, v104, v218, vcc
	v_cndmask_b32_e32 v11, v103, v218, vcc
	v_cmp_nlt_f32_e32 vcc, s0, v101
	s_nop 1
	v_cvt_pk_bf16_f32 v11, v104, v11
	s_and_saveexec_b64 s[0:1], vcc
	s_xor_b64 s[0:1], exec, s[0:1]
	v_mul_f32_e32 v57, 0x3fb8aa3b, v101
	v_exp_f32_e32 v57, v57
	s_nop 0
	v_sub_f32_e32 v57, 1.0, v57
	s_andn2_saveexec_b64 s[0:1], s[0:1]
	s_mov_b32 s2, 0x3e2aaaab
	v_fma_f32 v57, v101, s2, 0.5
	v_fma_f32 v57, v101, v57, 1.0
	v_mul_f32_e64 v57, v57, -v101
	s_or_b64 exec, exec, s[0:1]
	v_and_b32_e32 v101, 0xffff0000, v131
	v_mul_f32_e32 v101, v100, v101
	v_add_f32_e32 v102, v101, v101
	s_mov_b32 s0, 0xbca3d70a
	v_cmp_nlt_f32_e32 vcc, s0, v102
	s_and_saveexec_b64 s[0:1], vcc
	s_xor_b64 s[0:1], exec, s[0:1]
	v_mul_f32_e32 v102, 0x3fb8aa3b, v102
	v_exp_f32_e32 v102, v102
	s_nop 0
	v_sub_f32_e32 v103, 1.0, v102
	s_andn2_saveexec_b64 s[0:1], s[0:1]
	s_mov_b32 s2, 0x3e2aaaab
	v_fma_f32 v103, v102, s2, 0.5
	v_fma_f32 v103, v102, v103, 1.0
	v_mul_f32_e64 v103, v103, -v102
	s_or_b64 exec, exec, s[0:1]
	v_lshlrev_b32_e32 v102, 16, v130
	v_mul_f32_e32 v102, v22, v102
	v_add_f32_e32 v104, v102, v102
	s_mov_b32 s0, 0xbca3d70a
	v_cmp_nlt_f32_e32 vcc, s0, v104
	s_and_saveexec_b64 s[0:1], vcc
	s_xor_b64 s[0:1], exec, s[0:1]
	v_mul_f32_e32 v104, 0x3fb8aa3b, v104
	v_exp_f32_e32 v104, v104
	s_nop 0
	v_sub_f32_e32 v131, 1.0, v104
	s_andn2_saveexec_b64 s[0:1], s[0:1]
	s_mov_b32 s2, 0x3e2aaaab
	v_fma_f32 v105, v104, s2, 0.5
	v_fma_f32 v105, v104, v105, 1.0
	v_mul_f32_e64 v131, v105, -v104
	s_or_b64 exec, exec, s[0:1]
	v_and_b32_e32 v104, 0xffff0000, v130
	v_mul_f32_e32 v104, v23, v104
	v_add_f32_e32 v130, v104, v104
	s_mov_b32 s0, 0xbca3d70a
	v_cmp_nlt_f32_e32 vcc, s0, v130
	s_and_saveexec_b64 s[0:1], vcc
	s_xor_b64 s[0:1], exec, s[0:1]
	v_mul_f32_e32 v105, 0x3fb8aa3b, v130
	v_exp_f32_e32 v105, v105
	s_nop 0
	v_sub_f32_e32 v105, 1.0, v105
	s_andn2_saveexec_b64 s[0:1], s[0:1]
	s_mov_b32 s2, 0x3e2aaaab
	v_fma_f32 v105, v130, s2, 0.5
	v_fma_f32 v105, v130, v105, 1.0
	v_mul_f32_e64 v105, v105, -v130
	s_or_b64 exec, exec, s[0:1]
	v_add_f32_e32 v6, v6, v18
	v_mul_f32_e32 v6, 0xbfb8aa3b, v6
	v_add_f32_e32 v5, v5, v17
	v_exp_f32_e32 v6, v6
	v_mul_f32_e32 v5, 0xbfb8aa3b, v5
	v_exp_f32_e32 v5, v5
	v_max_f32_e32 v130, v131, v131
	v_max_f32_e32 v130, 0, v130
	v_add_f32_e32 v6, 1.0, v6
	v_add_f32_e32 v7, v7, v19
	v_max_f32_e32 v103, v103, v103
	v_sqrt_f32_e32 v130, v130
	v_rcp_f32_e32 v6, v6
	v_mul_f32_e32 v7, 0xbfb8aa3b, v7
	v_add_f32_e32 v5, 1.0, v5
	v_max_f32_e32 v103, 0, v103
	v_exp_f32_e32 v7, v7
	v_rcp_f32_e32 v5, v5
	v_sqrt_f32_e32 v103, v103
	v_add_f32_e32 v4, v4, v16
	v_mul_f32_e32 v4, 0xbfb8aa3b, v4
	v_exp_f32_e32 v4, v4
	s_waitcnt lgkmcnt(0)
	v_lshlrev_b32_e32 v131, 16, v21
	v_mul_f32_e32 v6, v6, v130
	v_mul_f32_e32 v130, v6, v131
	v_add_f32_e32 v6, 1.0, v7
	v_and_b32_e32 v7, 0xffff0000, v20
	v_mul_f32_e32 v5, v5, v103
	v_mul_f32_e32 v5, v5, v7
	v_lshlrev_b32_e32 v7, 16, v20
	v_max_f32_e32 v20, v57, v57
	v_add_f32_e32 v4, 1.0, v4
	v_max_f32_e32 v20, 0, v20
	v_max_f32_e32 v57, v105, v105
	v_rcp_f32_e32 v4, v4
	v_sqrt_f32_e32 v20, v20
	v_max_f32_e32 v57, 0, v57
	v_rcp_f32_e32 v6, v6
	v_sqrt_f32_e32 v57, v57
	v_mul_f32_e32 v4, v4, v20
	v_mul_f32_e32 v4, v4, v7
	v_and_b32_e32 v7, 0xffff0000, v21
	v_mul_f32_e32 v6, v6, v57
	v_mul_f32_e32 v20, v6, v7
	s_nop 1
	v_cvt_pk_bf16_f32 v4, v4, v5
	s_nop 1
	v_cvt_pk_bf16_f32 v5, v130, v20
	ds_read_b64 v[20:21], v59 offset:6144
	s_nop 1
	v_cvt_pk_bf16_f32 v6, v56, v101
	v_lshlrev_b32_e32 v56, 16, v129
	v_mul_f32_e32 v56, v58, v56
	v_add_f32_e32 v57, v56, v56
	s_mov_b32 s0, 0xbca3d70a
	v_cmp_nlt_f32_e32 vcc, s0, v57
	s_nop 1
	v_cvt_pk_bf16_f32 v7, v102, v104
	s_and_saveexec_b64 s[0:1], vcc
	s_xor_b64 s[0:1], exec, s[0:1]
	v_mul_f32_e32 v57, 0x3fb8aa3b, v57
	v_exp_f32_e32 v57, v57
	s_nop 0
	v_sub_f32_e32 v58, 1.0, v57
	s_andn2_saveexec_b64 s[0:1], s[0:1]
	s_mov_b32 s2, 0x3e2aaaab
	v_fma_f32 v58, v57, s2, 0.5
	v_fma_f32 v58, v57, v58, 1.0
	v_mul_f32_e64 v58, v58, -v57
	s_or_b64 exec, exec, s[0:1]
	v_and_b32_e32 v57, 0xffff0000, v129
	v_mul_f32_e32 v57, v100, v57
	v_add_f32_e32 v59, v57, v57
	s_mov_b32 s0, 0xbca3d70a
	v_cmp_nlt_f32_e32 vcc, s0, v59
	s_and_saveexec_b64 s[0:1], vcc
	s_xor_b64 s[0:1], exec, s[0:1]
	v_mul_f32_e32 v59, 0x3fb8aa3b, v59
	v_exp_f32_e32 v59, v59
	s_nop 0
	v_sub_f32_e32 v100, 1.0, v59
	s_andn2_saveexec_b64 s[0:1], s[0:1]
	s_mov_b32 s2, 0x3e2aaaab
	v_fma_f32 v100, v59, s2, 0.5
	v_fma_f32 v100, v59, v100, 1.0
	v_mul_f32_e64 v100, v100, -v59
	s_or_b64 exec, exec, s[0:1]
	v_lshlrev_b32_e32 v59, 16, v128
	v_mul_f32_e32 v22, v22, v59
	v_add_f32_e32 v59, v22, v22
	s_mov_b32 s0, 0xbca3d70a
	v_cmp_nlt_f32_e32 vcc, s0, v59
	s_and_saveexec_b64 s[0:1], vcc
	s_xor_b64 s[0:1], exec, s[0:1]
	v_mul_f32_e32 v59, 0x3fb8aa3b, v59
	v_exp_f32_e32 v59, v59
	s_nop 0
	v_sub_f32_e32 v101, 1.0, v59
	s_andn2_saveexec_b64 s[0:1], s[0:1]
	s_mov_b32 s2, 0x3e2aaaab
	v_fma_f32 v101, v59, s2, 0.5
	v_fma_f32 v101, v59, v101, 1.0
	v_mul_f32_e64 v101, v101, -v59
	s_or_b64 exec, exec, s[0:1]
	v_and_b32_e32 v59, 0xffff0000, v128
	v_mul_f32_e32 v23, v23, v59
	v_add_f32_e32 v102, v23, v23
	s_mov_b32 s0, 0xbca3d70a
	v_cmp_nlt_f32_e32 vcc, s0, v102
	s_and_saveexec_b64 s[0:1], vcc
	s_xor_b64 s[0:1], exec, s[0:1]
	v_mul_f32_e32 v59, 0x3fb8aa3b, v102
	v_exp_f32_e32 v59, v59
	s_nop 0
	v_sub_f32_e32 v59, 1.0, v59
	s_andn2_saveexec_b64 s[0:1], s[0:1]
	s_cbranch_execz .LBB0_1035
	s_mov_b32 s2, 0x3e2aaaab
	v_fma_f32 v59, v102, s2, 0.5
	v_fma_f32 v59, v102, v59, 1.0
	v_mul_f32_e64 v59, v59, -v102
	s_branch .LBB0_1035
